# GEMM tiles: peel first K iteration (first MFMA per accumulator takes C=0) instead of 128 v_mov zeroing per tile; plus mod loop 16 loads in flight
# speedup vs baseline: 1.0158x; 1.0052x over previous
; DI void phase_mod(PrmC p, unsigned char* smem) {
;     ...
;         for (int k = 0; k < 128; ++k) { const float4 wv = *(const float4*)(w + (size_t)k * 9216);
; #pragma unroll
;             for (int a = 0; a < 9; ++a) { const float sv = s_sh[a * 1024 + ks * 128 + k]; acc[a][0] += sv * wv.x; acc[a][1] += sv * wv.y; acc[a][2] += sv * wv.z; acc[a][3] += sv * wv.w; } }
.LBB0_41:
	v_lshl_add_u64 v[250:251], v[54:55], 0, s[6:7]
	global_load_dwordx4 v[122:125], v[250:251], off
	v_add_co_u32_e64 v250, s[4:5], s16, v250
	s_nop 1
	v_addc_co_u32_e64 v251, s[4:5], 0, v251, s[4:5]
	global_load_dwordx4 v[126:129], v[250:251], off
	v_add_co_u32_e64 v250, s[4:5], s16, v250
	s_nop 1
	v_addc_co_u32_e64 v251, s[4:5], 0, v251, s[4:5]
	global_load_dwordx4 v[130:133], v[250:251], off
	v_add_co_u32_e64 v250, s[4:5], s16, v250
	s_nop 1
	v_addc_co_u32_e64 v251, s[4:5], 0, v251, s[4:5]
	global_load_dwordx4 v[134:137], v[250:251], off
	v_add_co_u32_e64 v250, s[4:5], s16, v250
	s_nop 1
	v_addc_co_u32_e64 v251, s[4:5], 0, v251, s[4:5]
	global_load_dwordx4 v[138:141], v[250:251], off
	v_add_co_u32_e64 v250, s[4:5], s16, v250
	s_nop 1
	v_addc_co_u32_e64 v251, s[4:5], 0, v251, s[4:5]
	global_load_dwordx4 v[142:145], v[250:251], off
	v_add_co_u32_e64 v250, s[4:5], s16, v250
	s_nop 1
	v_addc_co_u32_e64 v251, s[4:5], 0, v251, s[4:5]
	global_load_dwordx4 v[146:149], v[250:251], off
	v_add_co_u32_e64 v250, s[4:5], s16, v250
	s_nop 1
	v_addc_co_u32_e64 v251, s[4:5], 0, v251, s[4:5]
	global_load_dwordx4 v[150:153], v[250:251], off
	v_add_co_u32_e64 v250, s[4:5], s16, v250
	s_nop 1
	v_addc_co_u32_e64 v251, s[4:5], 0, v251, s[4:5]
	global_load_dwordx4 v[154:157], v[250:251], off
	v_add_co_u32_e64 v250, s[4:5], s16, v250
	s_nop 1
	v_addc_co_u32_e64 v251, s[4:5], 0, v251, s[4:5]
	global_load_dwordx4 v[158:161], v[250:251], off
	v_add_co_u32_e64 v250, s[4:5], s16, v250
	s_nop 1
	v_addc_co_u32_e64 v251, s[4:5], 0, v251, s[4:5]
	global_load_dwordx4 v[162:165], v[250:251], off
	v_add_co_u32_e64 v250, s[4:5], s16, v250
	s_nop 1
	v_addc_co_u32_e64 v251, s[4:5], 0, v251, s[4:5]
	global_load_dwordx4 v[166:169], v[250:251], off
	v_add_co_u32_e64 v250, s[4:5], s16, v250
	s_nop 1
	v_addc_co_u32_e64 v251, s[4:5], 0, v251, s[4:5]
	global_load_dwordx4 v[170:173], v[250:251], off
	v_add_co_u32_e64 v250, s[4:5], s16, v250
	s_nop 1
	v_addc_co_u32_e64 v251, s[4:5], 0, v251, s[4:5]
	global_load_dwordx4 v[174:177], v[250:251], off
	v_add_co_u32_e64 v250, s[4:5], s16, v250
	s_nop 1
	v_addc_co_u32_e64 v251, s[4:5], 0, v251, s[4:5]
	global_load_dwordx4 v[178:181], v[250:251], off
	v_add_co_u32_e64 v250, s[4:5], s16, v250
	s_nop 1
	v_addc_co_u32_e64 v251, s[4:5], 0, v251, s[4:5]
	global_load_dwordx4 v[182:185], v[250:251], off
	s_add_u32 s6, s6, 0x90000
	s_addc_u32 s7, s7, 0
	ds_read_b128 v[38:41], v58
	ds_read_b128 v[42:45], v58 offset:32768
	ds_read_b128 v[60:63], v58 offset:4096
	ds_read_b128 v[64:67], v58 offset:8192
	ds_read_b128 v[68:71], v58 offset:12288
	ds_read_b128 v[72:75], v58 offset:16384
	ds_read_b128 v[76:79], v58 offset:20480
	ds_read_b128 v[80:83], v58 offset:24576
	ds_read_b128 v[84:87], v58 offset:28672
	s_waitcnt lgkmcnt(0)
	v_mov_b32_e32 v104, v41
	v_mov_b32_e32 v106, v63
	v_mov_b32_e32 v108, v67
	v_mov_b32_e32 v110, v71
	v_mov_b32_e32 v112, v75
	v_mov_b32_e32 v114, v79
	v_mov_b32_e32 v116, v83
	v_mov_b32_e32 v118, v87
	v_mov_b32_e32 v120, v45
	v_add_u32_e32 v58, 16, v58
	s_waitcnt vmcnt(15)
	v_pk_fma_f32 v[34:35], v[122:123], v[38:39], v[34:35] op_sel_hi:[1,0,1]
	v_pk_fma_f32 v[36:37], v[124:125], v[38:39], v[36:37] op_sel_hi:[1,0,1]
	v_pk_fma_f32 v[30:31], v[122:123], v[60:61], v[30:31] op_sel_hi:[1,0,1]
	v_pk_fma_f32 v[32:33], v[124:125], v[60:61], v[32:33] op_sel_hi:[1,0,1]
	v_pk_fma_f32 v[26:27], v[122:123], v[64:65], v[26:27] op_sel_hi:[1,0,1]
	v_pk_fma_f32 v[28:29], v[124:125], v[64:65], v[28:29] op_sel_hi:[1,0,1]
	v_pk_fma_f32 v[22:23], v[122:123], v[68:69], v[22:23] op_sel_hi:[1,0,1]
	v_pk_fma_f32 v[24:25], v[124:125], v[68:69], v[24:25] op_sel_hi:[1,0,1]
	v_pk_fma_f32 v[18:19], v[122:123], v[72:73], v[18:19] op_sel_hi:[1,0,1]
	v_pk_fma_f32 v[20:21], v[124:125], v[72:73], v[20:21] op_sel_hi:[1,0,1]
	v_pk_fma_f32 v[14:15], v[122:123], v[76:77], v[14:15] op_sel_hi:[1,0,1]
	v_pk_fma_f32 v[16:17], v[124:125], v[76:77], v[16:17] op_sel_hi:[1,0,1]
	v_pk_fma_f32 v[10:11], v[122:123], v[80:81], v[10:11] op_sel_hi:[1,0,1]
	v_pk_fma_f32 v[12:13], v[124:125], v[80:81], v[12:13] op_sel_hi:[1,0,1]
	v_pk_fma_f32 v[6:7], v[122:123], v[84:85], v[6:7] op_sel_hi:[1,0,1]
	v_pk_fma_f32 v[8:9], v[124:125], v[84:85], v[8:9] op_sel_hi:[1,0,1]
	v_pk_fma_f32 v[2:3], v[122:123], v[42:43], v[2:3] op_sel_hi:[1,0,1]
	v_pk_fma_f32 v[4:5], v[124:125], v[42:43], v[4:5] op_sel_hi:[1,0,1]
	s_waitcnt vmcnt(14)
	v_pk_fma_f32 v[34:35], v[126:127], v[38:39], v[34:35] op_sel:[0,1,0]
	v_pk_fma_f32 v[36:37], v[128:129], v[38:39], v[36:37] op_sel:[0,1,0]
	v_pk_fma_f32 v[30:31], v[126:127], v[60:61], v[30:31] op_sel:[0,1,0]
	v_pk_fma_f32 v[32:33], v[128:129], v[60:61], v[32:33] op_sel:[0,1,0]
	v_pk_fma_f32 v[26:27], v[126:127], v[64:65], v[26:27] op_sel:[0,1,0]
	v_pk_fma_f32 v[28:29], v[128:129], v[64:65], v[28:29] op_sel:[0,1,0]
	v_pk_fma_f32 v[22:23], v[126:127], v[68:69], v[22:23] op_sel:[0,1,0]
	v_pk_fma_f32 v[24:25], v[128:129], v[68:69], v[24:25] op_sel:[0,1,0]
	v_pk_fma_f32 v[18:19], v[126:127], v[72:73], v[18:19] op_sel:[0,1,0]
	v_pk_fma_f32 v[20:21], v[128:129], v[72:73], v[20:21] op_sel:[0,1,0]
	v_pk_fma_f32 v[14:15], v[126:127], v[76:77], v[14:15] op_sel:[0,1,0]
	v_pk_fma_f32 v[16:17], v[128:129], v[76:77], v[16:17] op_sel:[0,1,0]
	v_pk_fma_f32 v[10:11], v[126:127], v[80:81], v[10:11] op_sel:[0,1,0]
	v_pk_fma_f32 v[12:13], v[128:129], v[80:81], v[12:13] op_sel:[0,1,0]
	v_pk_fma_f32 v[6:7], v[126:127], v[84:85], v[6:7] op_sel:[0,1,0]
	v_pk_fma_f32 v[8:9], v[128:129], v[84:85], v[8:9] op_sel:[0,1,0]
	v_pk_fma_f32 v[2:3], v[126:127], v[42:43], v[2:3] op_sel:[0,1,0]
	v_pk_fma_f32 v[4:5], v[128:129], v[42:43], v[4:5] op_sel:[0,1,0]
	s_waitcnt vmcnt(13)
; DI void phase_mod(PrmC p, unsigned char* smem) {
;     ...
;         for (int k = 0; k < 128; ++k) { const float4 wv = *(const float4*)(w + (size_t)k * 9216);
; #pragma unroll
;             for (int a = 0; a < 9; ++a) { const float sv = s_sh[a * 1024 + ks * 128 + k]; acc[a][0] += sv * wv.x; acc[a][1] += sv * wv.y; acc[a][2] += sv * wv.z; acc[a][3] += sv * wv.w; } }
	v_pk_fma_f32 v[34:35], v[130:131], v[40:41], v[34:35] op_sel_hi:[1,0,1]
	v_pk_fma_f32 v[36:37], v[132:133], v[40:41], v[36:37] op_sel_hi:[1,0,1]
	v_pk_fma_f32 v[30:31], v[130:131], v[62:63], v[30:31] op_sel_hi:[1,0,1]
	v_pk_fma_f32 v[32:33], v[132:133], v[62:63], v[32:33] op_sel_hi:[1,0,1]
	v_pk_fma_f32 v[26:27], v[130:131], v[66:67], v[26:27] op_sel_hi:[1,0,1]
	v_pk_fma_f32 v[28:29], v[132:133], v[66:67], v[28:29] op_sel_hi:[1,0,1]
	v_pk_fma_f32 v[22:23], v[130:131], v[70:71], v[22:23] op_sel_hi:[1,0,1]
	v_pk_fma_f32 v[24:25], v[132:133], v[70:71], v[24:25] op_sel_hi:[1,0,1]
	v_pk_fma_f32 v[18:19], v[130:131], v[74:75], v[18:19] op_sel_hi:[1,0,1]
	v_pk_fma_f32 v[20:21], v[132:133], v[74:75], v[20:21] op_sel_hi:[1,0,1]
	v_pk_fma_f32 v[14:15], v[130:131], v[78:79], v[14:15] op_sel_hi:[1,0,1]
	v_pk_fma_f32 v[16:17], v[132:133], v[78:79], v[16:17] op_sel_hi:[1,0,1]
	v_pk_fma_f32 v[10:11], v[130:131], v[82:83], v[10:11] op_sel_hi:[1,0,1]
	v_pk_fma_f32 v[12:13], v[132:133], v[82:83], v[12:13] op_sel_hi:[1,0,1]
	v_pk_fma_f32 v[6:7], v[130:131], v[86:87], v[6:7] op_sel_hi:[1,0,1]
	v_pk_fma_f32 v[8:9], v[132:133], v[86:87], v[8:9] op_sel_hi:[1,0,1]
	v_pk_fma_f32 v[2:3], v[130:131], v[44:45], v[2:3] op_sel_hi:[1,0,1]
	v_pk_fma_f32 v[4:5], v[132:133], v[44:45], v[4:5] op_sel_hi:[1,0,1]
	s_waitcnt vmcnt(12)
	v_pk_fma_f32 v[34:35], v[134:135], v[104:105], v[34:35] op_sel_hi:[1,0,1]
	v_pk_fma_f32 v[36:37], v[136:137], v[104:105], v[36:37] op_sel_hi:[1,0,1]
	v_pk_fma_f32 v[30:31], v[134:135], v[106:107], v[30:31] op_sel_hi:[1,0,1]
	v_pk_fma_f32 v[32:33], v[136:137], v[106:107], v[32:33] op_sel_hi:[1,0,1]
	v_pk_fma_f32 v[26:27], v[134:135], v[108:109], v[26:27] op_sel_hi:[1,0,1]
	v_pk_fma_f32 v[28:29], v[136:137], v[108:109], v[28:29] op_sel_hi:[1,0,1]
	v_pk_fma_f32 v[22:23], v[134:135], v[110:111], v[22:23] op_sel_hi:[1,0,1]
	v_pk_fma_f32 v[24:25], v[136:137], v[110:111], v[24:25] op_sel_hi:[1,0,1]
	v_pk_fma_f32 v[18:19], v[134:135], v[112:113], v[18:19] op_sel_hi:[1,0,1]
	v_pk_fma_f32 v[20:21], v[136:137], v[112:113], v[20:21] op_sel_hi:[1,0,1]
	v_pk_fma_f32 v[14:15], v[134:135], v[114:115], v[14:15] op_sel_hi:[1,0,1]
	v_pk_fma_f32 v[16:17], v[136:137], v[114:115], v[16:17] op_sel_hi:[1,0,1]
	v_pk_fma_f32 v[10:11], v[134:135], v[116:117], v[10:11] op_sel_hi:[1,0,1]
	v_pk_fma_f32 v[12:13], v[136:137], v[116:117], v[12:13] op_sel_hi:[1,0,1]
	v_pk_fma_f32 v[6:7], v[134:135], v[118:119], v[6:7] op_sel_hi:[1,0,1]
	v_pk_fma_f32 v[8:9], v[136:137], v[118:119], v[8:9] op_sel_hi:[1,0,1]
	v_pk_fma_f32 v[2:3], v[134:135], v[120:121], v[2:3] op_sel_hi:[1,0,1]
	v_pk_fma_f32 v[4:5], v[136:137], v[120:121], v[4:5] op_sel_hi:[1,0,1]
	ds_read_b128 v[38:41], v58
	ds_read_b128 v[42:45], v58 offset:32768
	ds_read_b128 v[60:63], v58 offset:4096
	ds_read_b128 v[64:67], v58 offset:8192
	ds_read_b128 v[68:71], v58 offset:12288
	ds_read_b128 v[72:75], v58 offset:16384
	ds_read_b128 v[76:79], v58 offset:20480
	ds_read_b128 v[80:83], v58 offset:24576
	ds_read_b128 v[84:87], v58 offset:28672
	s_waitcnt lgkmcnt(0)
	v_mov_b32_e32 v104, v41
	v_mov_b32_e32 v106, v63
	v_mov_b32_e32 v108, v67
	v_mov_b32_e32 v110, v71
	v_mov_b32_e32 v112, v75
	v_mov_b32_e32 v114, v79
	v_mov_b32_e32 v116, v83
	v_mov_b32_e32 v118, v87
	v_mov_b32_e32 v120, v45
	v_add_u32_e32 v58, 16, v58
	s_waitcnt vmcnt(11)
	v_pk_fma_f32 v[34:35], v[138:139], v[38:39], v[34:35] op_sel_hi:[1,0,1]
	v_pk_fma_f32 v[36:37], v[140:141], v[38:39], v[36:37] op_sel_hi:[1,0,1]
	v_pk_fma_f32 v[30:31], v[138:139], v[60:61], v[30:31] op_sel_hi:[1,0,1]
	v_pk_fma_f32 v[32:33], v[140:141], v[60:61], v[32:33] op_sel_hi:[1,0,1]
	v_pk_fma_f32 v[26:27], v[138:139], v[64:65], v[26:27] op_sel_hi:[1,0,1]
	v_pk_fma_f32 v[28:29], v[140:141], v[64:65], v[28:29] op_sel_hi:[1,0,1]
	v_pk_fma_f32 v[22:23], v[138:139], v[68:69], v[22:23] op_sel_hi:[1,0,1]
	v_pk_fma_f32 v[24:25], v[140:141], v[68:69], v[24:25] op_sel_hi:[1,0,1]
	v_pk_fma_f32 v[18:19], v[138:139], v[72:73], v[18:19] op_sel_hi:[1,0,1]
	v_pk_fma_f32 v[20:21], v[140:141], v[72:73], v[20:21] op_sel_hi:[1,0,1]
	v_pk_fma_f32 v[14:15], v[138:139], v[76:77], v[14:15] op_sel_hi:[1,0,1]
	v_pk_fma_f32 v[16:17], v[140:141], v[76:77], v[16:17] op_sel_hi:[1,0,1]
	v_pk_fma_f32 v[10:11], v[138:139], v[80:81], v[10:11] op_sel_hi:[1,0,1]
	v_pk_fma_f32 v[12:13], v[140:141], v[80:81], v[12:13] op_sel_hi:[1,0,1]
	v_pk_fma_f32 v[6:7], v[138:139], v[84:85], v[6:7] op_sel_hi:[1,0,1]
	v_pk_fma_f32 v[8:9], v[140:141], v[84:85], v[8:9] op_sel_hi:[1,0,1]
	v_pk_fma_f32 v[2:3], v[138:139], v[42:43], v[2:3] op_sel_hi:[1,0,1]
	v_pk_fma_f32 v[4:5], v[140:141], v[42:43], v[4:5] op_sel_hi:[1,0,1]
	s_waitcnt vmcnt(10)
	v_pk_fma_f32 v[34:35], v[142:143], v[38:39], v[34:35] op_sel:[0,1,0]
	v_pk_fma_f32 v[36:37], v[144:145], v[38:39], v[36:37] op_sel:[0,1,0]
	v_pk_fma_f32 v[30:31], v[142:143], v[60:61], v[30:31] op_sel:[0,1,0]
	v_pk_fma_f32 v[32:33], v[144:145], v[60:61], v[32:33] op_sel:[0,1,0]
	v_pk_fma_f32 v[26:27], v[142:143], v[64:65], v[26:27] op_sel:[0,1,0]
	v_pk_fma_f32 v[28:29], v[144:145], v[64:65], v[28:29] op_sel:[0,1,0]
	v_pk_fma_f32 v[22:23], v[142:143], v[68:69], v[22:23] op_sel:[0,1,0]
	v_pk_fma_f32 v[24:25], v[144:145], v[68:69], v[24:25] op_sel:[0,1,0]
	v_pk_fma_f32 v[18:19], v[142:143], v[72:73], v[18:19] op_sel:[0,1,0]
	v_pk_fma_f32 v[20:21], v[144:145], v[72:73], v[20:21] op_sel:[0,1,0]
	v_pk_fma_f32 v[14:15], v[142:143], v[76:77], v[14:15] op_sel:[0,1,0]
	v_pk_fma_f32 v[16:17], v[144:145], v[76:77], v[16:17] op_sel:[0,1,0]
	v_pk_fma_f32 v[10:11], v[142:143], v[80:81], v[10:11] op_sel:[0,1,0]
	v_pk_fma_f32 v[12:13], v[144:145], v[80:81], v[12:13] op_sel:[0,1,0]
	v_pk_fma_f32 v[6:7], v[142:143], v[84:85], v[6:7] op_sel:[0,1,0]
	v_pk_fma_f32 v[8:9], v[144:145], v[84:85], v[8:9] op_sel:[0,1,0]
	v_pk_fma_f32 v[2:3], v[142:143], v[42:43], v[2:3] op_sel:[0,1,0]
	v_pk_fma_f32 v[4:5], v[144:145], v[42:43], v[4:5] op_sel:[0,1,0]
	s_waitcnt vmcnt(9)
; DI void phase_mod(PrmC p, unsigned char* smem) {
;     ...
;         for (int k = 0; k < 128; ++k) { const float4 wv = *(const float4*)(w + (size_t)k * 9216);
; #pragma unroll
;             for (int a = 0; a < 9; ++a) { const float sv = s_sh[a * 1024 + ks * 128 + k]; acc[a][0] += sv * wv.x; acc[a][1] += sv * wv.y; acc[a][2] += sv * wv.z; acc[a][3] += sv * wv.w; } }
	v_pk_fma_f32 v[34:35], v[146:147], v[40:41], v[34:35] op_sel_hi:[1,0,1]
	v_pk_fma_f32 v[36:37], v[148:149], v[40:41], v[36:37] op_sel_hi:[1,0,1]
	v_pk_fma_f32 v[30:31], v[146:147], v[62:63], v[30:31] op_sel_hi:[1,0,1]
	v_pk_fma_f32 v[32:33], v[148:149], v[62:63], v[32:33] op_sel_hi:[1,0,1]
	v_pk_fma_f32 v[26:27], v[146:147], v[66:67], v[26:27] op_sel_hi:[1,0,1]
	v_pk_fma_f32 v[28:29], v[148:149], v[66:67], v[28:29] op_sel_hi:[1,0,1]
	v_pk_fma_f32 v[22:23], v[146:147], v[70:71], v[22:23] op_sel_hi:[1,0,1]
	v_pk_fma_f32 v[24:25], v[148:149], v[70:71], v[24:25] op_sel_hi:[1,0,1]
	v_pk_fma_f32 v[18:19], v[146:147], v[74:75], v[18:19] op_sel_hi:[1,0,1]
	v_pk_fma_f32 v[20:21], v[148:149], v[74:75], v[20:21] op_sel_hi:[1,0,1]
	v_pk_fma_f32 v[14:15], v[146:147], v[78:79], v[14:15] op_sel_hi:[1,0,1]
	v_pk_fma_f32 v[16:17], v[148:149], v[78:79], v[16:17] op_sel_hi:[1,0,1]
	v_pk_fma_f32 v[10:11], v[146:147], v[82:83], v[10:11] op_sel_hi:[1,0,1]
	v_pk_fma_f32 v[12:13], v[148:149], v[82:83], v[12:13] op_sel_hi:[1,0,1]
	v_pk_fma_f32 v[6:7], v[146:147], v[86:87], v[6:7] op_sel_hi:[1,0,1]
	v_pk_fma_f32 v[8:9], v[148:149], v[86:87], v[8:9] op_sel_hi:[1,0,1]
	v_pk_fma_f32 v[2:3], v[146:147], v[44:45], v[2:3] op_sel_hi:[1,0,1]
	v_pk_fma_f32 v[4:5], v[148:149], v[44:45], v[4:5] op_sel_hi:[1,0,1]
	s_waitcnt vmcnt(8)
	v_pk_fma_f32 v[34:35], v[150:151], v[104:105], v[34:35] op_sel_hi:[1,0,1]
	v_pk_fma_f32 v[36:37], v[152:153], v[104:105], v[36:37] op_sel_hi:[1,0,1]
	v_pk_fma_f32 v[30:31], v[150:151], v[106:107], v[30:31] op_sel_hi:[1,0,1]
	v_pk_fma_f32 v[32:33], v[152:153], v[106:107], v[32:33] op_sel_hi:[1,0,1]
	v_pk_fma_f32 v[26:27], v[150:151], v[108:109], v[26:27] op_sel_hi:[1,0,1]
	v_pk_fma_f32 v[28:29], v[152:153], v[108:109], v[28:29] op_sel_hi:[1,0,1]
	v_pk_fma_f32 v[22:23], v[150:151], v[110:111], v[22:23] op_sel_hi:[1,0,1]
	v_pk_fma_f32 v[24:25], v[152:153], v[110:111], v[24:25] op_sel_hi:[1,0,1]
	v_pk_fma_f32 v[18:19], v[150:151], v[112:113], v[18:19] op_sel_hi:[1,0,1]
	v_pk_fma_f32 v[20:21], v[152:153], v[112:113], v[20:21] op_sel_hi:[1,0,1]
	v_pk_fma_f32 v[14:15], v[150:151], v[114:115], v[14:15] op_sel_hi:[1,0,1]
	v_pk_fma_f32 v[16:17], v[152:153], v[114:115], v[16:17] op_sel_hi:[1,0,1]
	v_pk_fma_f32 v[10:11], v[150:151], v[116:117], v[10:11] op_sel_hi:[1,0,1]
	v_pk_fma_f32 v[12:13], v[152:153], v[116:117], v[12:13] op_sel_hi:[1,0,1]
	v_pk_fma_f32 v[6:7], v[150:151], v[118:119], v[6:7] op_sel_hi:[1,0,1]
	v_pk_fma_f32 v[8:9], v[152:153], v[118:119], v[8:9] op_sel_hi:[1,0,1]
	v_pk_fma_f32 v[2:3], v[150:151], v[120:121], v[2:3] op_sel_hi:[1,0,1]
	v_pk_fma_f32 v[4:5], v[152:153], v[120:121], v[4:5] op_sel_hi:[1,0,1]
	ds_read_b128 v[38:41], v58
	ds_read_b128 v[42:45], v58 offset:32768
	ds_read_b128 v[60:63], v58 offset:4096
	ds_read_b128 v[64:67], v58 offset:8192
	ds_read_b128 v[68:71], v58 offset:12288
	ds_read_b128 v[72:75], v58 offset:16384
	ds_read_b128 v[76:79], v58 offset:20480
	ds_read_b128 v[80:83], v58 offset:24576
	ds_read_b128 v[84:87], v58 offset:28672
	s_waitcnt lgkmcnt(0)
	v_mov_b32_e32 v104, v41
	v_mov_b32_e32 v106, v63
	v_mov_b32_e32 v108, v67
	v_mov_b32_e32 v110, v71
	v_mov_b32_e32 v112, v75
	v_mov_b32_e32 v114, v79
	v_mov_b32_e32 v116, v83
	v_mov_b32_e32 v118, v87
	v_mov_b32_e32 v120, v45
	v_add_u32_e32 v58, 16, v58
	s_waitcnt vmcnt(7)
	v_pk_fma_f32 v[34:35], v[154:155], v[38:39], v[34:35] op_sel_hi:[1,0,1]
	v_pk_fma_f32 v[36:37], v[156:157], v[38:39], v[36:37] op_sel_hi:[1,0,1]
	v_pk_fma_f32 v[30:31], v[154:155], v[60:61], v[30:31] op_sel_hi:[1,0,1]
	v_pk_fma_f32 v[32:33], v[156:157], v[60:61], v[32:33] op_sel_hi:[1,0,1]
	v_pk_fma_f32 v[26:27], v[154:155], v[64:65], v[26:27] op_sel_hi:[1,0,1]
	v_pk_fma_f32 v[28:29], v[156:157], v[64:65], v[28:29] op_sel_hi:[1,0,1]
	v_pk_fma_f32 v[22:23], v[154:155], v[68:69], v[22:23] op_sel_hi:[1,0,1]
	v_pk_fma_f32 v[24:25], v[156:157], v[68:69], v[24:25] op_sel_hi:[1,0,1]
	v_pk_fma_f32 v[18:19], v[154:155], v[72:73], v[18:19] op_sel_hi:[1,0,1]
	v_pk_fma_f32 v[20:21], v[156:157], v[72:73], v[20:21] op_sel_hi:[1,0,1]
	v_pk_fma_f32 v[14:15], v[154:155], v[76:77], v[14:15] op_sel_hi:[1,0,1]
	v_pk_fma_f32 v[16:17], v[156:157], v[76:77], v[16:17] op_sel_hi:[1,0,1]
	v_pk_fma_f32 v[10:11], v[154:155], v[80:81], v[10:11] op_sel_hi:[1,0,1]
	v_pk_fma_f32 v[12:13], v[156:157], v[80:81], v[12:13] op_sel_hi:[1,0,1]
	v_pk_fma_f32 v[6:7], v[154:155], v[84:85], v[6:7] op_sel_hi:[1,0,1]
	v_pk_fma_f32 v[8:9], v[156:157], v[84:85], v[8:9] op_sel_hi:[1,0,1]
	v_pk_fma_f32 v[2:3], v[154:155], v[42:43], v[2:3] op_sel_hi:[1,0,1]
	v_pk_fma_f32 v[4:5], v[156:157], v[42:43], v[4:5] op_sel_hi:[1,0,1]
	s_waitcnt vmcnt(6)
	v_pk_fma_f32 v[34:35], v[158:159], v[38:39], v[34:35] op_sel:[0,1,0]
	v_pk_fma_f32 v[36:37], v[160:161], v[38:39], v[36:37] op_sel:[0,1,0]
	v_pk_fma_f32 v[30:31], v[158:159], v[60:61], v[30:31] op_sel:[0,1,0]
	v_pk_fma_f32 v[32:33], v[160:161], v[60:61], v[32:33] op_sel:[0,1,0]
	v_pk_fma_f32 v[26:27], v[158:159], v[64:65], v[26:27] op_sel:[0,1,0]
	v_pk_fma_f32 v[28:29], v[160:161], v[64:65], v[28:29] op_sel:[0,1,0]
	v_pk_fma_f32 v[22:23], v[158:159], v[68:69], v[22:23] op_sel:[0,1,0]
	v_pk_fma_f32 v[24:25], v[160:161], v[68:69], v[24:25] op_sel:[0,1,0]
	v_pk_fma_f32 v[18:19], v[158:159], v[72:73], v[18:19] op_sel:[0,1,0]
	v_pk_fma_f32 v[20:21], v[160:161], v[72:73], v[20:21] op_sel:[0,1,0]
	v_pk_fma_f32 v[14:15], v[158:159], v[76:77], v[14:15] op_sel:[0,1,0]
	v_pk_fma_f32 v[16:17], v[160:161], v[76:77], v[16:17] op_sel:[0,1,0]
	v_pk_fma_f32 v[10:11], v[158:159], v[80:81], v[10:11] op_sel:[0,1,0]
	v_pk_fma_f32 v[12:13], v[160:161], v[80:81], v[12:13] op_sel:[0,1,0]
	v_pk_fma_f32 v[6:7], v[158:159], v[84:85], v[6:7] op_sel:[0,1,0]
	v_pk_fma_f32 v[8:9], v[160:161], v[84:85], v[8:9] op_sel:[0,1,0]
	v_pk_fma_f32 v[2:3], v[158:159], v[42:43], v[2:3] op_sel:[0,1,0]
	v_pk_fma_f32 v[4:5], v[160:161], v[42:43], v[4:5] op_sel:[0,1,0]
	s_waitcnt vmcnt(5)
; DI void phase_mod(PrmC p, unsigned char* smem) {
;     ...
;         for (int k = 0; k < 128; ++k) { const float4 wv = *(const float4*)(w + (size_t)k * 9216);
; #pragma unroll
;             for (int a = 0; a < 9; ++a) { const float sv = s_sh[a * 1024 + ks * 128 + k]; acc[a][0] += sv * wv.x; acc[a][1] += sv * wv.y; acc[a][2] += sv * wv.z; acc[a][3] += sv * wv.w; } }
	v_pk_fma_f32 v[34:35], v[162:163], v[40:41], v[34:35] op_sel_hi:[1,0,1]
	v_pk_fma_f32 v[36:37], v[164:165], v[40:41], v[36:37] op_sel_hi:[1,0,1]
	v_pk_fma_f32 v[30:31], v[162:163], v[62:63], v[30:31] op_sel_hi:[1,0,1]
	v_pk_fma_f32 v[32:33], v[164:165], v[62:63], v[32:33] op_sel_hi:[1,0,1]
	v_pk_fma_f32 v[26:27], v[162:163], v[66:67], v[26:27] op_sel_hi:[1,0,1]
	v_pk_fma_f32 v[28:29], v[164:165], v[66:67], v[28:29] op_sel_hi:[1,0,1]
	v_pk_fma_f32 v[22:23], v[162:163], v[70:71], v[22:23] op_sel_hi:[1,0,1]
	v_pk_fma_f32 v[24:25], v[164:165], v[70:71], v[24:25] op_sel_hi:[1,0,1]
	v_pk_fma_f32 v[18:19], v[162:163], v[74:75], v[18:19] op_sel_hi:[1,0,1]
	v_pk_fma_f32 v[20:21], v[164:165], v[74:75], v[20:21] op_sel_hi:[1,0,1]
	v_pk_fma_f32 v[14:15], v[162:163], v[78:79], v[14:15] op_sel_hi:[1,0,1]
	v_pk_fma_f32 v[16:17], v[164:165], v[78:79], v[16:17] op_sel_hi:[1,0,1]
	v_pk_fma_f32 v[10:11], v[162:163], v[82:83], v[10:11] op_sel_hi:[1,0,1]
	v_pk_fma_f32 v[12:13], v[164:165], v[82:83], v[12:13] op_sel_hi:[1,0,1]
	v_pk_fma_f32 v[6:7], v[162:163], v[86:87], v[6:7] op_sel_hi:[1,0,1]
	v_pk_fma_f32 v[8:9], v[164:165], v[86:87], v[8:9] op_sel_hi:[1,0,1]
	v_pk_fma_f32 v[2:3], v[162:163], v[44:45], v[2:3] op_sel_hi:[1,0,1]
	v_pk_fma_f32 v[4:5], v[164:165], v[44:45], v[4:5] op_sel_hi:[1,0,1]
	s_waitcnt vmcnt(4)
	v_pk_fma_f32 v[34:35], v[166:167], v[104:105], v[34:35] op_sel_hi:[1,0,1]
	v_pk_fma_f32 v[36:37], v[168:169], v[104:105], v[36:37] op_sel_hi:[1,0,1]
	v_pk_fma_f32 v[30:31], v[166:167], v[106:107], v[30:31] op_sel_hi:[1,0,1]
	v_pk_fma_f32 v[32:33], v[168:169], v[106:107], v[32:33] op_sel_hi:[1,0,1]
	v_pk_fma_f32 v[26:27], v[166:167], v[108:109], v[26:27] op_sel_hi:[1,0,1]
	v_pk_fma_f32 v[28:29], v[168:169], v[108:109], v[28:29] op_sel_hi:[1,0,1]
	v_pk_fma_f32 v[22:23], v[166:167], v[110:111], v[22:23] op_sel_hi:[1,0,1]
	v_pk_fma_f32 v[24:25], v[168:169], v[110:111], v[24:25] op_sel_hi:[1,0,1]
	v_pk_fma_f32 v[18:19], v[166:167], v[112:113], v[18:19] op_sel_hi:[1,0,1]
	v_pk_fma_f32 v[20:21], v[168:169], v[112:113], v[20:21] op_sel_hi:[1,0,1]
	v_pk_fma_f32 v[14:15], v[166:167], v[114:115], v[14:15] op_sel_hi:[1,0,1]
	v_pk_fma_f32 v[16:17], v[168:169], v[114:115], v[16:17] op_sel_hi:[1,0,1]
	v_pk_fma_f32 v[10:11], v[166:167], v[116:117], v[10:11] op_sel_hi:[1,0,1]
	v_pk_fma_f32 v[12:13], v[168:169], v[116:117], v[12:13] op_sel_hi:[1,0,1]
	v_pk_fma_f32 v[6:7], v[166:167], v[118:119], v[6:7] op_sel_hi:[1,0,1]
	v_pk_fma_f32 v[8:9], v[168:169], v[118:119], v[8:9] op_sel_hi:[1,0,1]
	v_pk_fma_f32 v[2:3], v[166:167], v[120:121], v[2:3] op_sel_hi:[1,0,1]
	v_pk_fma_f32 v[4:5], v[168:169], v[120:121], v[4:5] op_sel_hi:[1,0,1]
	ds_read_b128 v[38:41], v58
	ds_read_b128 v[42:45], v58 offset:32768
	ds_read_b128 v[60:63], v58 offset:4096
	ds_read_b128 v[64:67], v58 offset:8192
	ds_read_b128 v[68:71], v58 offset:12288
	ds_read_b128 v[72:75], v58 offset:16384
	ds_read_b128 v[76:79], v58 offset:20480
	ds_read_b128 v[80:83], v58 offset:24576
	ds_read_b128 v[84:87], v58 offset:28672
	s_waitcnt lgkmcnt(0)
	v_mov_b32_e32 v104, v41
	v_mov_b32_e32 v106, v63
	v_mov_b32_e32 v108, v67
	v_mov_b32_e32 v110, v71
	v_mov_b32_e32 v112, v75
	v_mov_b32_e32 v114, v79
	v_mov_b32_e32 v116, v83
	v_mov_b32_e32 v118, v87
	v_mov_b32_e32 v120, v45
	v_add_u32_e32 v58, 16, v58
	s_waitcnt vmcnt(3)
	v_pk_fma_f32 v[34:35], v[170:171], v[38:39], v[34:35] op_sel_hi:[1,0,1]
	v_pk_fma_f32 v[36:37], v[172:173], v[38:39], v[36:37] op_sel_hi:[1,0,1]
	v_pk_fma_f32 v[30:31], v[170:171], v[60:61], v[30:31] op_sel_hi:[1,0,1]
	v_pk_fma_f32 v[32:33], v[172:173], v[60:61], v[32:33] op_sel_hi:[1,0,1]
	v_pk_fma_f32 v[26:27], v[170:171], v[64:65], v[26:27] op_sel_hi:[1,0,1]
	v_pk_fma_f32 v[28:29], v[172:173], v[64:65], v[28:29] op_sel_hi:[1,0,1]
	v_pk_fma_f32 v[22:23], v[170:171], v[68:69], v[22:23] op_sel_hi:[1,0,1]
	v_pk_fma_f32 v[24:25], v[172:173], v[68:69], v[24:25] op_sel_hi:[1,0,1]
	v_pk_fma_f32 v[18:19], v[170:171], v[72:73], v[18:19] op_sel_hi:[1,0,1]
	v_pk_fma_f32 v[20:21], v[172:173], v[72:73], v[20:21] op_sel_hi:[1,0,1]
	v_pk_fma_f32 v[14:15], v[170:171], v[76:77], v[14:15] op_sel_hi:[1,0,1]
	v_pk_fma_f32 v[16:17], v[172:173], v[76:77], v[16:17] op_sel_hi:[1,0,1]
	v_pk_fma_f32 v[10:11], v[170:171], v[80:81], v[10:11] op_sel_hi:[1,0,1]
	v_pk_fma_f32 v[12:13], v[172:173], v[80:81], v[12:13] op_sel_hi:[1,0,1]
	v_pk_fma_f32 v[6:7], v[170:171], v[84:85], v[6:7] op_sel_hi:[1,0,1]
	v_pk_fma_f32 v[8:9], v[172:173], v[84:85], v[8:9] op_sel_hi:[1,0,1]
	v_pk_fma_f32 v[2:3], v[170:171], v[42:43], v[2:3] op_sel_hi:[1,0,1]
	v_pk_fma_f32 v[4:5], v[172:173], v[42:43], v[4:5] op_sel_hi:[1,0,1]
	s_waitcnt vmcnt(2)
; DI void phase_mod(PrmC p, unsigned char* smem) {
;     ...
;         for (int k = 0; k < 128; ++k) { const float4 wv = *(const float4*)(w + (size_t)k * 9216);
; #pragma unroll
;             for (int a = 0; a < 9; ++a) { const float sv = s_sh[a * 1024 + ks * 128 + k]; acc[a][0] += sv * wv.x; acc[a][1] += sv * wv.y; acc[a][2] += sv * wv.z; acc[a][3] += sv * wv.w; } }
; #pragma unroll
;         for (int a = 0; a < 9; ++a) *(float4*)(red + (ks * 9 + a) * 256 + lane * 4) = make_float4(acc[a][0], acc[a][1], acc[a][2], acc[a][3]);
;         __syncthreads();
;         for (int o = tid; o < 9 * 256; o += NTHR) { const int a = o >> 8, c = o & 255; float v = p->ada_b[l * 9216 + cb * 256 + c];
; #pragma unroll
;             for (int q = 0; q < 8; ++q) v += red[(q * 9 + a) * 256 + c];
;             MOD[((size_t)l * 9 + a) * 9216 + cb * 256 + c] = v; }
	v_pk_fma_f32 v[34:35], v[174:175], v[38:39], v[34:35] op_sel:[0,1,0]
	v_pk_fma_f32 v[36:37], v[176:177], v[38:39], v[36:37] op_sel:[0,1,0]
	v_pk_fma_f32 v[30:31], v[174:175], v[60:61], v[30:31] op_sel:[0,1,0]
	v_pk_fma_f32 v[32:33], v[176:177], v[60:61], v[32:33] op_sel:[0,1,0]
	v_pk_fma_f32 v[26:27], v[174:175], v[64:65], v[26:27] op_sel:[0,1,0]
	v_pk_fma_f32 v[28:29], v[176:177], v[64:65], v[28:29] op_sel:[0,1,0]
	v_pk_fma_f32 v[22:23], v[174:175], v[68:69], v[22:23] op_sel:[0,1,0]
	v_pk_fma_f32 v[24:25], v[176:177], v[68:69], v[24:25] op_sel:[0,1,0]
	v_pk_fma_f32 v[18:19], v[174:175], v[72:73], v[18:19] op_sel:[0,1,0]
	v_pk_fma_f32 v[20:21], v[176:177], v[72:73], v[20:21] op_sel:[0,1,0]
	v_pk_fma_f32 v[14:15], v[174:175], v[76:77], v[14:15] op_sel:[0,1,0]
	v_pk_fma_f32 v[16:17], v[176:177], v[76:77], v[16:17] op_sel:[0,1,0]
	v_pk_fma_f32 v[10:11], v[174:175], v[80:81], v[10:11] op_sel:[0,1,0]
	v_pk_fma_f32 v[12:13], v[176:177], v[80:81], v[12:13] op_sel:[0,1,0]
	v_pk_fma_f32 v[6:7], v[174:175], v[84:85], v[6:7] op_sel:[0,1,0]
	v_pk_fma_f32 v[8:9], v[176:177], v[84:85], v[8:9] op_sel:[0,1,0]
	v_pk_fma_f32 v[2:3], v[174:175], v[42:43], v[2:3] op_sel:[0,1,0]
	v_pk_fma_f32 v[4:5], v[176:177], v[42:43], v[4:5] op_sel:[0,1,0]
	s_waitcnt vmcnt(1)
	v_pk_fma_f32 v[34:35], v[178:179], v[40:41], v[34:35] op_sel_hi:[1,0,1]
	v_pk_fma_f32 v[36:37], v[180:181], v[40:41], v[36:37] op_sel_hi:[1,0,1]
	v_pk_fma_f32 v[30:31], v[178:179], v[62:63], v[30:31] op_sel_hi:[1,0,1]
	v_pk_fma_f32 v[32:33], v[180:181], v[62:63], v[32:33] op_sel_hi:[1,0,1]
	v_pk_fma_f32 v[26:27], v[178:179], v[66:67], v[26:27] op_sel_hi:[1,0,1]
	v_pk_fma_f32 v[28:29], v[180:181], v[66:67], v[28:29] op_sel_hi:[1,0,1]
	v_pk_fma_f32 v[22:23], v[178:179], v[70:71], v[22:23] op_sel_hi:[1,0,1]
	v_pk_fma_f32 v[24:25], v[180:181], v[70:71], v[24:25] op_sel_hi:[1,0,1]
	v_pk_fma_f32 v[18:19], v[178:179], v[74:75], v[18:19] op_sel_hi:[1,0,1]
	v_pk_fma_f32 v[20:21], v[180:181], v[74:75], v[20:21] op_sel_hi:[1,0,1]
	v_pk_fma_f32 v[14:15], v[178:179], v[78:79], v[14:15] op_sel_hi:[1,0,1]
	v_pk_fma_f32 v[16:17], v[180:181], v[78:79], v[16:17] op_sel_hi:[1,0,1]
	v_pk_fma_f32 v[10:11], v[178:179], v[82:83], v[10:11] op_sel_hi:[1,0,1]
	v_pk_fma_f32 v[12:13], v[180:181], v[82:83], v[12:13] op_sel_hi:[1,0,1]
	v_pk_fma_f32 v[6:7], v[178:179], v[86:87], v[6:7] op_sel_hi:[1,0,1]
	v_pk_fma_f32 v[8:9], v[180:181], v[86:87], v[8:9] op_sel_hi:[1,0,1]
	v_pk_fma_f32 v[2:3], v[178:179], v[44:45], v[2:3] op_sel_hi:[1,0,1]
	v_pk_fma_f32 v[4:5], v[180:181], v[44:45], v[4:5] op_sel_hi:[1,0,1]
	s_waitcnt vmcnt(0)
	v_pk_fma_f32 v[34:35], v[182:183], v[104:105], v[34:35] op_sel_hi:[1,0,1]
	v_pk_fma_f32 v[36:37], v[184:185], v[104:105], v[36:37] op_sel_hi:[1,0,1]
	v_pk_fma_f32 v[30:31], v[182:183], v[106:107], v[30:31] op_sel_hi:[1,0,1]
	v_pk_fma_f32 v[32:33], v[184:185], v[106:107], v[32:33] op_sel_hi:[1,0,1]
	v_pk_fma_f32 v[26:27], v[182:183], v[108:109], v[26:27] op_sel_hi:[1,0,1]
	v_pk_fma_f32 v[28:29], v[184:185], v[108:109], v[28:29] op_sel_hi:[1,0,1]
	v_pk_fma_f32 v[22:23], v[182:183], v[110:111], v[22:23] op_sel_hi:[1,0,1]
	v_pk_fma_f32 v[24:25], v[184:185], v[110:111], v[24:25] op_sel_hi:[1,0,1]
	v_pk_fma_f32 v[18:19], v[182:183], v[112:113], v[18:19] op_sel_hi:[1,0,1]
	v_pk_fma_f32 v[20:21], v[184:185], v[112:113], v[20:21] op_sel_hi:[1,0,1]
	v_pk_fma_f32 v[14:15], v[182:183], v[114:115], v[14:15] op_sel_hi:[1,0,1]
	v_pk_fma_f32 v[16:17], v[184:185], v[114:115], v[16:17] op_sel_hi:[1,0,1]
	v_pk_fma_f32 v[10:11], v[182:183], v[116:117], v[10:11] op_sel_hi:[1,0,1]
	v_pk_fma_f32 v[12:13], v[184:185], v[116:117], v[12:13] op_sel_hi:[1,0,1]
	v_pk_fma_f32 v[6:7], v[182:183], v[118:119], v[6:7] op_sel_hi:[1,0,1]
	v_pk_fma_f32 v[8:9], v[184:185], v[118:119], v[8:9] op_sel_hi:[1,0,1]
	v_pk_fma_f32 v[2:3], v[182:183], v[120:121], v[2:3] op_sel_hi:[1,0,1]
	v_pk_fma_f32 v[4:5], v[184:185], v[120:121], v[4:5] op_sel_hi:[1,0,1]
	s_cmp_lg_u32 s6, 0x480000
	s_cbranch_scc1 .LBB0_41
	ds_write_b128 v57, v[34:37]
	ds_write_b128 v57, v[30:33] offset:1024
	ds_write_b128 v57, v[26:29] offset:2048
	ds_write_b128 v57, v[22:25] offset:3072
	ds_write_b128 v57, v[18:21] offset:4096
	ds_write_b128 v57, v[14:17] offset:5120
	ds_write_b128 v57, v[10:13] offset:6144
	ds_write_b128 v57, v[6:9] offset:7168
	ds_write_b128 v57, v[2:5] offset:8192
	s_waitcnt lgkmcnt(0)
	s_barrier
	s_and_saveexec_b64 s[6:7], vcc
	s_cbranch_execz .LBB0_39
	s_mul_i32 s4, s8, 36
	s_sub_i32 s4, s3, s4
	s_load_dwordx2 s[14:15], s[10:11], 0x28
	s_lshl_b32 s4, s4, 8
	s_add_i32 s20, s9, s4
	v_or_b32_sdwa v2, s20, v46 dst_sel:DWORD dst_unused:UNUSED_PAD src0_sel:DWORD src1_sel:BYTE_0
	s_ashr_i32 s5, s4, 31
	v_ashrrev_i32_e32 v3, 31, v2
	s_mul_hi_i32 s9, s8, 9
	s_mul_i32 s8, s8, 9
	s_waitcnt lgkmcnt(0)
	v_lshl_add_u64 v[2:3], v[2:3], 2, s[14:15]
	v_lshl_add_u64 v[4:5], s[4:5], 2, v[50:51]
	s_mov_b64 s[14:15], 0
	v_mov_b32_e32 v6, v46

; #define PG8_STAGE(bufoff, gbase, voff) do { _Pragma("unroll") for (int _i = 0; _i < 2; ++_i) \
;         __builtin_amdgcn_global_load_lds((const unsigned*)((const char*)(gbase) + (voff)[_i]), (PG8_LAS unsigned*)(lds + (bufoff) + ldsw + _i * 8192), 16, 0, 0); } while (0)
; #define PG8_LDA(dst, b, h) do { _Pragma("unroll") for (int m = 0; m < 4; ++m) _Pragma("unroll") for (int k = 0; k < 2; ++k) dst[m][k] = *(const PG8_LAS bf16x8*)(lds + PG8_SA(b, h) + aoff + m * 2048 + k * 1024); } while (0)
; #define PG8_LDB(dst, b, h) do { _Pragma("unroll") for (int n = 0; n < 2; ++n) _Pragma("unroll") for (int k = 0; k < 2; ++k) dst[n][k] = *(const PG8_LAS bf16x8*)(lds + PG8_SB(b, h) + boff + n * 2048 + k * 1024); } while (0)
; #define PG8_MMA(ai, bj, At, Bt) do { __builtin_amdgcn_s_setprio(1); _Pragma("unroll") for (int m = 0; m < 4; ++m) _Pragma("unroll") for (int n = 0; n < 2; ++n) _Pragma("unroll") for (int k = 0; k < 2; ++k) \
;         acc[ai][bj][m][n] = __builtin_amdgcn_mfma_f32_16x16x32_bf16(Bt[n][k], At[m][k], acc[ai][bj][m][n], 0, 0, 0); __builtin_amdgcn_s_setprio(0); } while (0)
; #define PG8_WAIT_V(n) asm volatile("s_waitcnt vmcnt(" #n ")" ::: "memory")
; #define PG8_WAIT_L(n) asm volatile("s_waitcnt lgkmcnt(" #n ")" ::: "memory")
; #define PG8_BAR __builtin_amdgcn_s_barrier()
; #define PG8_SCHED __builtin_amdgcn_sched_barrier(0)
; template <class Epi, class Sched, bool ALIGN_EPI = false, bool SP2 = false>
; __device__ __forceinline__ void gemm_phase(PG8_LAS unsigned char* lds, const Gemm g, const Sched& S, const Epi& E) {
;     ...
;             PG8_LDB(B0, 0, 0); PG8_LDB(B1, 0, 1); PG8_SCHED; PG8_LDA(At, 0, 0); PG8_STAGE(PG8_SA(1, 1), a1 + hstep, voffA);
;             PG8_WAIT_V(8); PG8_WAIT_L(0); PG8_BAR; PG8_MMA(0, 0, At, B0); PG8_MMA(0, 1, At, B1); PG8_BAR; PG8_SCHED;
;             PG8_LDA(At, 0, 1); PG8_STAGE(PG8_SB(0, 0), b2, voffB); PG8_STAGE(PG8_SB(0, 1), b2 + hstep, voffB); PG8_STAGE(PG8_SA(0, 0), a2, voffA);
;             PG8_WAIT_V(8); PG8_WAIT_L(0); PG8_BAR; PG8_MMA(1, 0, At, B0); PG8_MMA(1, 1, At, B1); PG8_BAR; PG8_SCHED;
.LBB0_766:
	s_ashr_i32 s17, s16, 31
	s_lshl_b64 s[20:21], s[16:17], 19
	s_add_u32 s20, s77, s20
	s_addc_u32 s21, s26, s21
	s_and_b64 s[30:31], s[6:7], exec
	s_cselect_b32 s17, s21, s39
	s_cselect_b32 s48, s20, s38
	s_ashr_i32 s15, s14, 31
	s_lshl_b64 s[30:31], s[14:15], 19
	v_readlane_b32 s42, v255, 18
	v_readlane_b32 s43, v255, 19
	s_add_u32 s30, s42, s30
	s_addc_u32 s31, s43, s31
	s_and_b64 s[42:43], s[6:7], exec
	s_cselect_b32 s15, s31, s41
	s_cselect_b32 s49, s30, s40
	s_add_u32 s38, s38, 0x40080
	s_addc_u32 s39, s39, 0
	s_add_u32 s50, s40, 0x100
	s_addc_u32 s51, s41, 0
	s_mov_b32 s54, -2
	s_add_u32 s40, s38, 0xfffc0080
	s_addc_u32 s41, s39, -1
	s_add_i32 s55, 0, 0x10000
	s_cmp_eq_u32 s54, 12
	s_cselect_b32 s43, s17, s41
	s_cselect_b32 s42, s48, s40
	v_add_u32_e32 v140, s55, v143
	s_cselect_b32 s41, s15, s51
	s_cselect_b32 s40, s49, s50
	s_add_i32 s63, 0, 0x14000
	ds_read_b128 v[146:149], v140
	ds_read_b128 v[150:153], v140 offset:1024
	ds_read_b128 v[154:157], v140 offset:2048
	ds_read_b128 v[158:161], v140 offset:3072
	v_add_u32_e32 v140, s63, v143
	ds_read_b128 v[162:165], v140
	ds_read_b128 v[166:169], v140 offset:1024
	ds_read_b128 v[170:173], v140 offset:2048
	ds_read_b128 v[174:177], v140 offset:3072
	v_lshl_add_u64 v[140:141], s[38:39], 0, v[136:137]
	s_add_i32 m0, s19, 0xc000
	ds_read_b128 v[178:181], v145
	ds_read_b128 v[182:185], v145 offset:1024
	ds_read_b128 v[186:189], v145 offset:2048
	ds_read_b128 v[190:193], v145 offset:3072
	ds_read_b128 v[198:201], v145 offset:4096
	ds_read_b128 v[202:205], v145 offset:5120
	ds_read_b128 v[206:209], v145 offset:6144
	ds_read_b128 v[210:213], v145 offset:7168
	global_load_lds_dwordx4 v[140:141], off
	v_lshl_add_u64 v[140:141], s[38:39], 0, v[138:139]
	s_add_i32 m0, s19, 0xe000
	s_nop 0
	global_load_lds_dwordx4 v[140:141], off
	s_waitcnt vmcnt(8)
	s_waitcnt lgkmcnt(0)
	s_barrier
	s_setprio 1
	s_waitcnt lgkmcnt(0)
	v_mfma_f32_16x16x32_bf16 v[126:129], v[146:149], v[178:181], 0
	v_mfma_f32_16x16x32_bf16 v[122:125], v[154:157], v[178:181], 0
	v_mfma_f32_16x16x32_bf16 v[118:121], v[146:149], v[186:189], 0
	v_mfma_f32_16x16x32_bf16 v[110:113], v[154:157], v[186:189], 0
	v_mfma_f32_16x16x32_bf16 v[102:105], v[146:149], v[198:201], 0
	v_mfma_f32_16x16x32_bf16 v[94:97], v[154:157], v[198:201], 0
	v_mfma_f32_16x16x32_bf16 v[86:89], v[146:149], v[206:209], 0
	v_mfma_f32_16x16x32_bf16 v[78:81], v[154:157], v[206:209], 0
	v_mfma_f32_16x16x32_bf16 v[126:129], v[150:153], v[182:185], v[126:129]
	v_mfma_f32_16x16x32_bf16 v[122:125], v[158:161], v[182:185], v[122:125]
	v_mfma_f32_16x16x32_bf16 v[118:121], v[150:153], v[190:193], v[118:121]
	v_mfma_f32_16x16x32_bf16 v[110:113], v[158:161], v[190:193], v[110:113]
	v_mfma_f32_16x16x32_bf16 v[102:105], v[150:153], v[202:205], v[102:105]
	v_mfma_f32_16x16x32_bf16 v[94:97], v[158:161], v[202:205], v[94:97]
	v_mfma_f32_16x16x32_bf16 v[86:89], v[150:153], v[210:213], v[86:89]
	v_mfma_f32_16x16x32_bf16 v[78:81], v[158:161], v[210:213], v[78:81]
	s_setprio 0
	s_setprio 1
	v_mfma_f32_16x16x32_bf16 v[114:117], v[162:165], v[178:181], 0
	v_mfma_f32_16x16x32_bf16 v[106:109], v[170:173], v[178:181], 0
	v_mfma_f32_16x16x32_bf16 v[98:101], v[162:165], v[186:189], 0
	v_mfma_f32_16x16x32_bf16 v[90:93], v[170:173], v[186:189], 0
	v_mfma_f32_16x16x32_bf16 v[82:85], v[162:165], v[198:201], 0
	v_mfma_f32_16x16x32_bf16 v[74:77], v[170:173], v[198:201], 0
	v_mfma_f32_16x16x32_bf16 v[70:73], v[162:165], v[206:209], 0
	v_mfma_f32_16x16x32_bf16 v[66:69], v[170:173], v[206:209], 0
	v_mfma_f32_16x16x32_bf16 v[114:117], v[166:169], v[182:185], v[114:117]
	v_mfma_f32_16x16x32_bf16 v[106:109], v[174:177], v[182:185], v[106:109]
	v_mfma_f32_16x16x32_bf16 v[98:101], v[166:169], v[190:193], v[98:101]
	v_mfma_f32_16x16x32_bf16 v[90:93], v[174:177], v[190:193], v[90:93]
	v_mfma_f32_16x16x32_bf16 v[82:85], v[166:169], v[202:205], v[82:85]
	v_mfma_f32_16x16x32_bf16 v[74:77], v[174:177], v[202:205], v[74:77]
	v_mfma_f32_16x16x32_bf16 v[70:73], v[166:169], v[210:213], v[70:73]
	v_mfma_f32_16x16x32_bf16 v[66:69], v[174:177], v[210:213], v[66:69]
	s_setprio 0
	s_barrier
	s_add_i32 s55, s55, s5
	v_lshl_add_u64 v[140:141], s[40:41], 0, v[0:1]
	s_mov_b32 m0, s55
	ds_read_b128 v[178:181], v145 offset:16384
	ds_read_b128 v[182:185], v145 offset:17408
	ds_read_b128 v[186:189], v145 offset:18432
	ds_read_b128 v[190:193], v145 offset:19456
	ds_read_b128 v[198:201], v145 offset:20480
	ds_read_b128 v[202:205], v145 offset:21504
	ds_read_b128 v[206:209], v145 offset:22528
	ds_read_b128 v[210:213], v145 offset:23552
	global_load_lds_dwordx4 v[140:141], off
	s_add_i32 m0, s55, 0x2000
	s_add_u32 s72, s40, 0x40000
	v_lshl_add_u64 v[214:215], s[40:41], 0, v[130:131]
	s_addc_u32 s73, s41, 0
	s_add_i32 s55, s63, s5
	global_load_lds_dwordx4 v[214:215], off
	v_lshl_add_u64 v[216:217], s[72:73], 0, v[0:1]
	s_mov_b32 m0, s55
	v_lshl_add_u64 v[218:219], s[42:43], 0, v[132:133]
	global_load_lds_dwordx4 v[216:217], off
	v_lshl_add_u64 v[216:217], s[72:73], 0, v[130:131]
	s_add_i32 m0, s55, 0x2000
	s_nop 0
	global_load_lds_dwordx4 v[216:217], off
	v_lshl_add_u64 v[216:217], s[42:43], 0, v[134:135]
	s_mov_b32 m0, s19
	s_nop 0
	global_load_lds_dwordx4 v[216:217], off
	s_mov_b32 m0, s27
	s_nop 0
	global_load_lds_dwordx4 v[218:219], off
	s_waitcnt vmcnt(8)
	s_waitcnt lgkmcnt(0)
	s_barrier
; #define PG8_STAGE(bufoff, gbase, voff) do { _Pragma("unroll") for (int _i = 0; _i < 2; ++_i) \
;         __builtin_amdgcn_global_load_lds((const unsigned*)((const char*)(gbase) + (voff)[_i]), (PG8_LAS unsigned*)(lds + (bufoff) + ldsw + _i * 8192), 16, 0, 0); } while (0)
; #define PG8_LDA(dst, b, h) do { _Pragma("unroll") for (int m = 0; m < 4; ++m) _Pragma("unroll") for (int k = 0; k < 2; ++k) dst[m][k] = *(const PG8_LAS bf16x8*)(lds + PG8_SA(b, h) + aoff + m * 2048 + k * 1024); } while (0)
; #define PG8_LDB(dst, b, h) do { _Pragma("unroll") for (int n = 0; n < 2; ++n) _Pragma("unroll") for (int k = 0; k < 2; ++k) dst[n][k] = *(const PG8_LAS bf16x8*)(lds + PG8_SB(b, h) + boff + n * 2048 + k * 1024); } while (0)
; #define PG8_MMA(ai, bj, At, Bt) do { __builtin_amdgcn_s_setprio(1); _Pragma("unroll") for (int m = 0; m < 4; ++m) _Pragma("unroll") for (int n = 0; n < 2; ++n) _Pragma("unroll") for (int k = 0; k < 2; ++k) \
;         acc[ai][bj][m][n] = __builtin_amdgcn_mfma_f32_16x16x32_bf16(Bt[n][k], At[m][k], acc[ai][bj][m][n], 0, 0, 0); __builtin_amdgcn_s_setprio(0); } while (0)
; #define PG8_WAIT_V(n) asm volatile("s_waitcnt vmcnt(" #n ")" ::: "memory")
; #define PG8_WAIT_L(n) asm volatile("s_waitcnt lgkmcnt(" #n ")" ::: "memory")
; #define PG8_BAR __builtin_amdgcn_s_barrier()
; #define PG8_SCHED __builtin_amdgcn_sched_barrier(0)
; template <class Epi, class Sched, bool ALIGN_EPI = false, bool SP2 = false>
; __device__ __forceinline__ void gemm_phase(PG8_LAS unsigned char* lds, const Gemm g, const Sched& S, const Epi& E) {
;     ...
;             PG8_WAIT_V(8); PG8_WAIT_L(0); PG8_BAR; PG8_MMA(1, 0, At, B0); PG8_MMA(1, 1, At, B1); PG8_BAR; PG8_SCHED;
;             PG8_LDB(B0, 1, 0); PG8_LDB(B1, 1, 1); PG8_SCHED; PG8_LDA(At, 1, 0); PG8_STAGE(PG8_SA(0, 1), a2 + hstep, voffA);
;             PG8_WAIT_V(8); PG8_WAIT_L(0); PG8_BAR; PG8_MMA(0, 0, At, B0); PG8_MMA(0, 1, At, B1); PG8_BAR; PG8_SCHED;
	s_setprio 1
	s_waitcnt lgkmcnt(0)
	v_mfma_f32_16x16x32_bf16 v[62:65], v[146:149], v[178:181], 0
	v_mfma_f32_16x16x32_bf16 v[58:61], v[154:157], v[178:181], 0
	v_mfma_f32_16x16x32_bf16 v[54:57], v[146:149], v[186:189], 0
	v_mfma_f32_16x16x32_bf16 v[46:49], v[154:157], v[186:189], 0
	v_mfma_f32_16x16x32_bf16 v[38:41], v[146:149], v[198:201], 0
	v_mfma_f32_16x16x32_bf16 v[30:33], v[154:157], v[198:201], 0
	v_mfma_f32_16x16x32_bf16 v[22:25], v[146:149], v[206:209], 0
	v_mfma_f32_16x16x32_bf16 v[14:17], v[154:157], v[206:209], 0
	v_mfma_f32_16x16x32_bf16 v[62:65], v[150:153], v[182:185], v[62:65]
	v_mfma_f32_16x16x32_bf16 v[58:61], v[158:161], v[182:185], v[58:61]
	v_mfma_f32_16x16x32_bf16 v[54:57], v[150:153], v[190:193], v[54:57]
	v_mfma_f32_16x16x32_bf16 v[46:49], v[158:161], v[190:193], v[46:49]
	v_mfma_f32_16x16x32_bf16 v[38:41], v[150:153], v[202:205], v[38:41]
	v_mfma_f32_16x16x32_bf16 v[30:33], v[158:161], v[202:205], v[30:33]
	v_mfma_f32_16x16x32_bf16 v[22:25], v[150:153], v[210:213], v[22:25]
	v_mfma_f32_16x16x32_bf16 v[14:17], v[158:161], v[210:213], v[14:17]
	s_setprio 0
	s_setprio 1
	v_mfma_f32_16x16x32_bf16 v[50:53], v[162:165], v[178:181], 0
	v_mfma_f32_16x16x32_bf16 v[42:45], v[170:173], v[178:181], 0
	v_mfma_f32_16x16x32_bf16 v[34:37], v[162:165], v[186:189], 0
	v_mfma_f32_16x16x32_bf16 v[26:29], v[170:173], v[186:189], 0
	v_mfma_f32_16x16x32_bf16 v[18:21], v[162:165], v[198:201], 0
	v_mfma_f32_16x16x32_bf16 v[10:13], v[170:173], v[198:201], 0
	v_mfma_f32_16x16x32_bf16 v[6:9], v[162:165], v[206:209], 0
	v_mfma_f32_16x16x32_bf16 v[2:5], v[170:173], v[206:209], 0
	v_mfma_f32_16x16x32_bf16 v[50:53], v[166:169], v[182:185], v[50:53]
	v_mfma_f32_16x16x32_bf16 v[42:45], v[174:177], v[182:185], v[42:45]
	v_mfma_f32_16x16x32_bf16 v[34:37], v[166:169], v[190:193], v[34:37]
	v_mfma_f32_16x16x32_bf16 v[26:29], v[174:177], v[190:193], v[26:29]
	v_mfma_f32_16x16x32_bf16 v[18:21], v[166:169], v[202:205], v[18:21]
	v_mfma_f32_16x16x32_bf16 v[10:13], v[174:177], v[202:205], v[10:13]
	v_mfma_f32_16x16x32_bf16 v[6:9], v[166:169], v[210:213], v[6:9]
	v_mfma_f32_16x16x32_bf16 v[2:5], v[174:177], v[210:213], v[2:5]
	s_setprio 0
	s_barrier
	s_add_i32 s55, 0, 0x18000
	s_add_i32 s63, 0, 0x1c000
	v_add_u32_e32 v158, s55, v143
	v_add_u32_e32 v174, s63, v143
	ds_read_b128 v[146:149], v158
	ds_read_b128 v[150:153], v158 offset:1024
	ds_read_b128 v[154:157], v158 offset:2048
	ds_read_b128 v[158:161], v158 offset:3072
	ds_read_b128 v[162:165], v174
	ds_read_b128 v[166:169], v174 offset:1024
	ds_read_b128 v[170:173], v174 offset:2048
	ds_read_b128 v[174:177], v174 offset:3072
	s_add_u32 s42, s42, 0x40000
	s_addc_u32 s43, s43, 0
	s_mov_b32 m0, s28
	v_lshl_add_u64 v[220:221], s[42:43], 0, v[134:135]
	ds_read_b128 v[178:181], v145 offset:32768
	ds_read_b128 v[182:185], v145 offset:33792
	ds_read_b128 v[186:189], v145 offset:34816
	ds_read_b128 v[190:193], v145 offset:35840
	ds_read_b128 v[198:201], v145 offset:36864
	ds_read_b128 v[202:205], v145 offset:37888
	ds_read_b128 v[206:209], v145 offset:38912
	ds_read_b128 v[210:213], v145 offset:39936
	global_load_lds_dwordx4 v[220:221], off
	v_lshl_add_u64 v[220:221], s[42:43], 0, v[132:133]
	s_mov_b32 m0, s29
	s_nop 0
	global_load_lds_dwordx4 v[220:221], off
	s_waitcnt vmcnt(8)
	s_waitcnt lgkmcnt(0)
	s_barrier
	s_setprio 1
	s_waitcnt lgkmcnt(0)
	v_mfma_f32_16x16x32_bf16 v[126:129], v[146:149], v[178:181], v[126:129]
	v_mfma_f32_16x16x32_bf16 v[122:125], v[154:157], v[178:181], v[122:125]
	v_mfma_f32_16x16x32_bf16 v[118:121], v[146:149], v[186:189], v[118:121]
	v_mfma_f32_16x16x32_bf16 v[110:113], v[154:157], v[186:189], v[110:113]
	v_mfma_f32_16x16x32_bf16 v[102:105], v[146:149], v[198:201], v[102:105]
	v_mfma_f32_16x16x32_bf16 v[94:97], v[154:157], v[198:201], v[94:97]
	v_mfma_f32_16x16x32_bf16 v[86:89], v[146:149], v[206:209], v[86:89]
	v_mfma_f32_16x16x32_bf16 v[78:81], v[154:157], v[206:209], v[78:81]
	v_mfma_f32_16x16x32_bf16 v[126:129], v[150:153], v[182:185], v[126:129]
	v_mfma_f32_16x16x32_bf16 v[122:125], v[158:161], v[182:185], v[122:125]
	v_mfma_f32_16x16x32_bf16 v[118:121], v[150:153], v[190:193], v[118:121]
	v_mfma_f32_16x16x32_bf16 v[110:113], v[158:161], v[190:193], v[110:113]
	v_mfma_f32_16x16x32_bf16 v[102:105], v[150:153], v[202:205], v[102:105]
	v_mfma_f32_16x16x32_bf16 v[94:97], v[158:161], v[202:205], v[94:97]
	v_mfma_f32_16x16x32_bf16 v[86:89], v[150:153], v[210:213], v[86:89]
	v_mfma_f32_16x16x32_bf16 v[78:81], v[158:161], v[210:213], v[78:81]
	s_setprio 0
	s_setprio 1
	v_mfma_f32_16x16x32_bf16 v[114:117], v[162:165], v[178:181], v[114:117]
	v_mfma_f32_16x16x32_bf16 v[106:109], v[170:173], v[178:181], v[106:109]
	v_mfma_f32_16x16x32_bf16 v[98:101], v[162:165], v[186:189], v[98:101]
	v_mfma_f32_16x16x32_bf16 v[90:93], v[170:173], v[186:189], v[90:93]
	v_mfma_f32_16x16x32_bf16 v[82:85], v[162:165], v[198:201], v[82:85]
	v_mfma_f32_16x16x32_bf16 v[74:77], v[170:173], v[198:201], v[74:77]
	v_mfma_f32_16x16x32_bf16 v[70:73], v[162:165], v[206:209], v[70:73]
	v_mfma_f32_16x16x32_bf16 v[66:69], v[170:173], v[206:209], v[66:69]
	v_mfma_f32_16x16x32_bf16 v[114:117], v[166:169], v[182:185], v[114:117]
	v_mfma_f32_16x16x32_bf16 v[106:109], v[174:177], v[182:185], v[106:109]
	v_mfma_f32_16x16x32_bf16 v[98:101], v[166:169], v[190:193], v[98:101]
	v_mfma_f32_16x16x32_bf16 v[90:93], v[174:177], v[190:193], v[90:93]
	v_mfma_f32_16x16x32_bf16 v[82:85], v[166:169], v[202:205], v[82:85]
	v_mfma_f32_16x16x32_bf16 v[74:77], v[174:177], v[202:205], v[74:77]
	v_mfma_f32_16x16x32_bf16 v[70:73], v[166:169], v[210:213], v[70:73]
	v_mfma_f32_16x16x32_bf16 v[66:69], v[174:177], v[210:213], v[66:69]
	s_setprio 0
	s_barrier
; #define PG8_STAGE(bufoff, gbase, voff) do { _Pragma("unroll") for (int _i = 0; _i < 2; ++_i) \
;         __builtin_amdgcn_global_load_lds((const unsigned*)((const char*)(gbase) + (voff)[_i]), (PG8_LAS unsigned*)(lds + (bufoff) + ldsw + _i * 8192), 16, 0, 0); } while (0)
; #define PG8_LDA(dst, b, h) do { _Pragma("unroll") for (int m = 0; m < 4; ++m) _Pragma("unroll") for (int k = 0; k < 2; ++k) dst[m][k] = *(const PG8_LAS bf16x8*)(lds + PG8_SA(b, h) + aoff + m * 2048 + k * 1024); } while (0)
; #define PG8_MMA(ai, bj, At, Bt) do { __builtin_amdgcn_s_setprio(1); _Pragma("unroll") for (int m = 0; m < 4; ++m) _Pragma("unroll") for (int n = 0; n < 2; ++n) _Pragma("unroll") for (int k = 0; k < 2; ++k) \
;         acc[ai][bj][m][n] = __builtin_amdgcn_mfma_f32_16x16x32_bf16(Bt[n][k], At[m][k], acc[ai][bj][m][n], 0, 0, 0); __builtin_amdgcn_s_setprio(0); } while (0)
; #define PG8_WAIT_V(n) asm volatile("s_waitcnt vmcnt(" #n ")" ::: "memory")
; #define PG8_WAIT_L(n) asm volatile("s_waitcnt lgkmcnt(" #n ")" ::: "memory")
; #define PG8_BAR __builtin_amdgcn_s_barrier()
; #define PG8_SCHED __builtin_amdgcn_sched_barrier(0)
; template <class Epi, class Sched, bool ALIGN_EPI = false, bool SP2 = false>
; __device__ __forceinline__ void gemm_phase(PG8_LAS unsigned char* lds, const Gemm g, const Sched& S, const Epi& E) {
;     ...
;             PG8_LDA(At, 1, 1); PG8_STAGE(PG8_SB(1, 0), b3, voffB); PG8_STAGE(PG8_SB(1, 1), b3 + hstep, voffB); PG8_STAGE(PG8_SA(1, 0), a3, voffA);
;             PG8_WAIT_V(8); PG8_WAIT_L(0); PG8_BAR; PG8_MMA(1, 0, At, B0); PG8_MMA(1, 1, At, B1); PG8_BAR; PG8_SCHED;
	s_add_i32 s42, s55, s5
	v_lshl_add_u64 v[140:141], v[140:141], 0, s[58:59]
	s_mov_b32 m0, s42
	ds_read_b128 v[178:181], v145 offset:49152
	ds_read_b128 v[182:185], v145 offset:50176
	ds_read_b128 v[186:189], v145 offset:51200
	ds_read_b128 v[190:193], v145 offset:52224
	ds_read_b128 v[198:201], v145 offset:53248
	ds_read_b128 v[202:205], v145 offset:54272
	ds_read_b128 v[206:209], v145 offset:55296
	ds_read_b128 v[210:213], v145 offset:56320
	global_load_lds_dwordx4 v[140:141], off
	s_add_i32 m0, s42, 0x2000
	s_add_u32 s40, s40, 0x40080
	v_lshl_add_u64 v[140:141], v[214:215], 0, s[58:59]
	s_addc_u32 s41, s41, 0
	s_add_i32 s42, s63, s5
	global_load_lds_dwordx4 v[140:141], off
	v_lshl_add_u64 v[140:141], s[40:41], 0, v[0:1]
	s_mov_b32 m0, s42
	s_nop 0
	global_load_lds_dwordx4 v[140:141], off
	v_lshl_add_u64 v[140:141], s[40:41], 0, v[130:131]
	s_add_i32 m0, s42, 0x2000
	s_nop 0
	global_load_lds_dwordx4 v[140:141], off
	v_lshl_add_u64 v[140:141], v[216:217], 0, s[58:59]
	s_mov_b32 m0, s37
	s_nop 0
	global_load_lds_dwordx4 v[140:141], off
	v_lshl_add_u64 v[140:141], v[218:219], 0, s[58:59]
	s_mov_b32 m0, s44
	s_nop 0
	global_load_lds_dwordx4 v[140:141], off
	s_waitcnt vmcnt(8)
	s_waitcnt lgkmcnt(0)
	s_barrier
	s_setprio 1
	s_waitcnt lgkmcnt(0)
	v_mfma_f32_16x16x32_bf16 v[62:65], v[146:149], v[178:181], v[62:65]
	v_mfma_f32_16x16x32_bf16 v[58:61], v[154:157], v[178:181], v[58:61]
	v_mfma_f32_16x16x32_bf16 v[54:57], v[146:149], v[186:189], v[54:57]
	v_mfma_f32_16x16x32_bf16 v[46:49], v[154:157], v[186:189], v[46:49]
	v_mfma_f32_16x16x32_bf16 v[38:41], v[146:149], v[198:201], v[38:41]
	v_mfma_f32_16x16x32_bf16 v[30:33], v[154:157], v[198:201], v[30:33]
	v_mfma_f32_16x16x32_bf16 v[22:25], v[146:149], v[206:209], v[22:25]
	v_mfma_f32_16x16x32_bf16 v[14:17], v[154:157], v[206:209], v[14:17]
	v_mfma_f32_16x16x32_bf16 v[62:65], v[150:153], v[182:185], v[62:65]
	v_mfma_f32_16x16x32_bf16 v[58:61], v[158:161], v[182:185], v[58:61]
	v_mfma_f32_16x16x32_bf16 v[54:57], v[150:153], v[190:193], v[54:57]
	v_mfma_f32_16x16x32_bf16 v[46:49], v[158:161], v[190:193], v[46:49]
	v_mfma_f32_16x16x32_bf16 v[38:41], v[150:153], v[202:205], v[38:41]
	v_mfma_f32_16x16x32_bf16 v[30:33], v[158:161], v[202:205], v[30:33]
	v_mfma_f32_16x16x32_bf16 v[22:25], v[150:153], v[210:213], v[22:25]
	v_mfma_f32_16x16x32_bf16 v[14:17], v[158:161], v[210:213], v[14:17]
	s_setprio 0
	s_setprio 1
	v_mfma_f32_16x16x32_bf16 v[50:53], v[162:165], v[178:181], v[50:53]
	v_mfma_f32_16x16x32_bf16 v[42:45], v[170:173], v[178:181], v[42:45]
	v_mfma_f32_16x16x32_bf16 v[34:37], v[162:165], v[186:189], v[34:37]
	v_mfma_f32_16x16x32_bf16 v[26:29], v[170:173], v[186:189], v[26:29]
	v_mfma_f32_16x16x32_bf16 v[18:21], v[162:165], v[198:201], v[18:21]
	v_mfma_f32_16x16x32_bf16 v[10:13], v[170:173], v[198:201], v[10:13]
	v_mfma_f32_16x16x32_bf16 v[6:9], v[162:165], v[206:209], v[6:9]
	v_mfma_f32_16x16x32_bf16 v[2:5], v[170:173], v[206:209], v[2:5]
	v_mfma_f32_16x16x32_bf16 v[50:53], v[166:169], v[182:185], v[50:53]
	v_mfma_f32_16x16x32_bf16 v[42:45], v[174:177], v[182:185], v[42:45]
	v_mfma_f32_16x16x32_bf16 v[34:37], v[166:169], v[190:193], v[34:37]
	v_mfma_f32_16x16x32_bf16 v[26:29], v[174:177], v[190:193], v[26:29]
	v_mfma_f32_16x16x32_bf16 v[18:21], v[166:169], v[202:205], v[18:21]
	v_mfma_f32_16x16x32_bf16 v[10:13], v[174:177], v[202:205], v[10:13]
	v_mfma_f32_16x16x32_bf16 v[6:9], v[166:169], v[210:213], v[6:9]
	v_mfma_f32_16x16x32_bf16 v[2:5], v[174:177], v[210:213], v[2:5]
	s_setprio 0
	s_barrier
	s_add_i32 s54, s54, 2
	s_add_u32 s38, s38, 0x100
	s_addc_u32 s39, s39, 0
	s_add_u32 s50, s50, 0x100
	s_addc_u32 s51, s51, 0
	s_cmp_gt_u32 s54, 13
	s_cbranch_scc1 .Lpeel_done_767

; #define PG8_BAR __builtin_amdgcn_s_barrier()
; template <class Epi, class Sched, bool ALIGN_EPI = false, bool SP2 = false>
; __device__ __forceinline__ void gemm_phase(PG8_LAS unsigned char* lds, const Gemm g, const Sched& S, const Epi& E) {
;     ...
;         if constexpr (ALIGN_EPI) { if (wr == 0) PG8_BAR; }
;         if constexpr (!Epi::AFTER_DRAIN) { E(acc, cur, wr, wc, fr, fq); S.done(cur); }
.Lpeel_done_767:
	s_and_b64 vcc, exec, s[12:13]
	s_cbranch_vccz .LBB0_770
	s_barrier

; #define PG8_STAGE(bufoff, gbase, voff) do { _Pragma("unroll") for (int _i = 0; _i < 2; ++_i) \
;         __builtin_amdgcn_global_load_lds((const unsigned*)((const char*)(gbase) + (voff)[_i]), (PG8_LAS unsigned*)(lds + (bufoff) + ldsw + _i * 8192), 16, 0, 0); } while (0)
; #define PG8_LDA(dst, b, h) do { _Pragma("unroll") for (int m = 0; m < 4; ++m) _Pragma("unroll") for (int k = 0; k < 2; ++k) dst[m][k] = *(const PG8_LAS bf16x8*)(lds + PG8_SA(b, h) + aoff + m * 2048 + k * 1024); } while (0)
; #define PG8_LDB(dst, b, h) do { _Pragma("unroll") for (int n = 0; n < 2; ++n) _Pragma("unroll") for (int k = 0; k < 2; ++k) dst[n][k] = *(const PG8_LAS bf16x8*)(lds + PG8_SB(b, h) + boff + n * 2048 + k * 1024); } while (0)
; #define PG8_MMA(ai, bj, At, Bt) do { __builtin_amdgcn_s_setprio(1); _Pragma("unroll") for (int m = 0; m < 4; ++m) _Pragma("unroll") for (int n = 0; n < 2; ++n) _Pragma("unroll") for (int k = 0; k < 2; ++k) \
;         acc[ai][bj][m][n] = __builtin_amdgcn_mfma_f32_16x16x32_bf16(Bt[n][k], At[m][k], acc[ai][bj][m][n], 0, 0, 0); __builtin_amdgcn_s_setprio(0); } while (0)
; #define PG8_WAIT_V(n) asm volatile("s_waitcnt vmcnt(" #n ")" ::: "memory")
; #define PG8_WAIT_L(n) asm volatile("s_waitcnt lgkmcnt(" #n ")" ::: "memory")
; #define PG8_BAR __builtin_amdgcn_s_barrier()
; #define PG8_SCHED __builtin_amdgcn_sched_barrier(0)
; template <class Epi, class Sched, bool ALIGN_EPI = false, bool SP2 = false>
; __device__ __forceinline__ void gemm_phase(PG8_LAS unsigned char* lds, const Gemm g, const Sched& S, const Epi& E) {
;     ...
;             PG8_LDB(B0, 0, 0); PG8_LDB(B1, 0, 1); PG8_SCHED; PG8_LDA(At, 0, 0); PG8_STAGE(PG8_SA(1, 1), a1 + hstep, voffA);
;             PG8_WAIT_V(8); PG8_WAIT_L(0); PG8_BAR; PG8_MMA(0, 0, At, B0); PG8_MMA(0, 1, At, B1); PG8_BAR; PG8_SCHED;
;             PG8_LDA(At, 0, 1); PG8_STAGE(PG8_SB(0, 0), b2, voffB); PG8_STAGE(PG8_SB(0, 1), b2 + hstep, voffB); PG8_STAGE(PG8_SA(0, 0), a2, voffA);
;             PG8_WAIT_V(8); PG8_WAIT_L(0); PG8_BAR; PG8_MMA(1, 0, At, B0); PG8_MMA(1, 1, At, B1); PG8_BAR; PG8_SCHED;
.LBB0_806:
	s_add_u32 s38, s38, 0x80
	s_addc_u32 s39, s39, 0
	s_add_u32 s86, s40, 0x100
	s_addc_u32 s87, s41, 0
	s_mov_b32 s40, 0
	s_waitcnt vmcnt(0)
	s_add_i32 vcc_lo, s40, 2
	s_add_u32 s72, s38, 0x80
	s_addc_u32 s41, s39, 0
	s_add_i32 vcc_hi, 0, 0x10000
	s_cmp_eq_u32 s65, s40
	s_cselect_b32 s41, s9, s41
	s_cselect_b32 s40, s8, s72
	v_add_u32_e32 v0, vcc_hi, v250
	s_cselect_b32 s73, s11, s87
	s_cselect_b32 s72, s10, s86
	s_add_i32 s78, 0, 0x14000
	ds_read_b128 v[130:133], v0
	ds_read_b128 v[134:137], v0 offset:1024
	ds_read_b128 v[138:141], v0 offset:2048
	ds_read_b128 v[142:145], v0 offset:3072
	v_add_u32_e32 v0, s78, v250
	ds_read_b128 v[146:149], v0
	ds_read_b128 v[150:153], v0 offset:1024
	ds_read_b128 v[154:157], v0 offset:2048
	ds_read_b128 v[158:161], v0 offset:3072
	v_lshl_add_u64 v[210:211], s[38:39], 0, v[206:207]
	s_add_i32 m0, s47, 0xc000
	ds_read_b128 v[162:165], v252
	ds_read_b128 v[166:169], v252 offset:1024
	ds_read_b128 v[170:173], v252 offset:2048
	ds_read_b128 v[174:177], v252 offset:3072
	ds_read_b128 v[178:181], v252 offset:4096
	ds_read_b128 v[182:185], v252 offset:5120
	ds_read_b128 v[186:189], v252 offset:6144
	ds_read_b128 v[190:193], v252 offset:7168
	global_load_lds_dwordx4 v[210:211], off
	v_lshl_add_u64 v[210:211], s[38:39], 0, v[208:209]
	s_add_i32 m0, s47, 0xe000
	s_nop 0
	global_load_lds_dwordx4 v[210:211], off
	s_waitcnt vmcnt(8)
	s_waitcnt lgkmcnt(0)
	s_barrier
	s_setprio 1
	s_waitcnt lgkmcnt(0)
	v_mfma_f32_16x16x32_bf16 v[126:129], v[130:133], v[162:165], 0
	v_mfma_f32_16x16x32_bf16 v[122:125], v[138:141], v[162:165], 0
	v_mfma_f32_16x16x32_bf16 v[110:113], v[130:133], v[170:173], 0
	v_mfma_f32_16x16x32_bf16 v[106:109], v[138:141], v[170:173], 0
	v_mfma_f32_16x16x32_bf16 v[94:97], v[130:133], v[178:181], 0
	v_mfma_f32_16x16x32_bf16 v[90:93], v[138:141], v[178:181], 0
	v_mfma_f32_16x16x32_bf16 v[78:81], v[130:133], v[186:189], 0
	v_mfma_f32_16x16x32_bf16 v[74:77], v[138:141], v[186:189], 0
	v_mfma_f32_16x16x32_bf16 v[126:129], v[134:137], v[166:169], v[126:129]
	v_mfma_f32_16x16x32_bf16 v[122:125], v[142:145], v[166:169], v[122:125]
	v_mfma_f32_16x16x32_bf16 v[110:113], v[134:137], v[174:177], v[110:113]
	v_mfma_f32_16x16x32_bf16 v[106:109], v[142:145], v[174:177], v[106:109]
	v_mfma_f32_16x16x32_bf16 v[94:97], v[134:137], v[182:185], v[94:97]
	v_mfma_f32_16x16x32_bf16 v[90:93], v[142:145], v[182:185], v[90:93]
	v_mfma_f32_16x16x32_bf16 v[78:81], v[134:137], v[190:193], v[78:81]
	v_mfma_f32_16x16x32_bf16 v[74:77], v[142:145], v[190:193], v[74:77]
	s_setprio 0
	s_setprio 1
	v_mfma_f32_16x16x32_bf16 v[118:121], v[146:149], v[162:165], 0
	v_mfma_f32_16x16x32_bf16 v[114:117], v[154:157], v[162:165], 0
	v_mfma_f32_16x16x32_bf16 v[102:105], v[146:149], v[170:173], 0
	v_mfma_f32_16x16x32_bf16 v[98:101], v[154:157], v[170:173], 0
	v_mfma_f32_16x16x32_bf16 v[86:89], v[146:149], v[178:181], 0
	v_mfma_f32_16x16x32_bf16 v[82:85], v[154:157], v[178:181], 0
	v_mfma_f32_16x16x32_bf16 v[70:73], v[146:149], v[186:189], 0
	v_mfma_f32_16x16x32_bf16 v[66:69], v[154:157], v[186:189], 0
	v_mfma_f32_16x16x32_bf16 v[118:121], v[150:153], v[166:169], v[118:121]
	v_mfma_f32_16x16x32_bf16 v[114:117], v[158:161], v[166:169], v[114:117]
	v_mfma_f32_16x16x32_bf16 v[102:105], v[150:153], v[174:177], v[102:105]
	v_mfma_f32_16x16x32_bf16 v[98:101], v[158:161], v[174:177], v[98:101]
	v_mfma_f32_16x16x32_bf16 v[86:89], v[150:153], v[182:185], v[86:89]
	v_mfma_f32_16x16x32_bf16 v[82:85], v[158:161], v[182:185], v[82:85]
	v_mfma_f32_16x16x32_bf16 v[70:73], v[150:153], v[190:193], v[70:73]
	v_mfma_f32_16x16x32_bf16 v[66:69], v[158:161], v[190:193], v[66:69]
	s_setprio 0
	s_barrier
	s_add_i32 s79, vcc_hi, s44
	v_lshl_add_u64 v[210:211], s[72:73], 0, v[198:199]
	s_mov_b32 m0, s79
	ds_read_b128 v[162:165], v252 offset:16384
	ds_read_b128 v[166:169], v252 offset:17408
	ds_read_b128 v[170:173], v252 offset:18432
	ds_read_b128 v[174:177], v252 offset:19456
	ds_read_b128 v[178:181], v252 offset:20480
	ds_read_b128 v[182:185], v252 offset:21504
	ds_read_b128 v[186:189], v252 offset:22528
	ds_read_b128 v[190:193], v252 offset:23552
	global_load_lds_dwordx4 v[210:211], off
	s_add_i32 m0, s79, 0x2000
	v_lshl_add_u64 v[212:213], s[72:73], 0, v[200:201]
	s_add_u32 s72, s72, s30
	s_addc_u32 s73, s73, 0
	s_add_i32 s78, s78, s44
	global_load_lds_dwordx4 v[212:213], off
	v_lshl_add_u64 v[214:215], s[72:73], 0, v[198:199]
	s_mov_b32 m0, s78
	v_lshl_add_u64 v[216:217], s[72:73], 0, v[200:201]
	global_load_lds_dwordx4 v[214:215], off
	s_add_i32 m0, s78, 0x2000
	v_lshl_add_u64 v[218:219], s[40:41], 0, v[198:199]
	global_load_lds_dwordx4 v[216:217], off
	s_mov_b32 m0, s47
	v_lshl_add_u64 v[220:221], s[40:41], 0, v[200:201]
	global_load_lds_dwordx4 v[218:219], off
	s_mov_b32 m0, s48
	s_nop 0
	global_load_lds_dwordx4 v[220:221], off
	s_waitcnt vmcnt(8)
	s_waitcnt lgkmcnt(0)
	s_barrier
; #define PG8_STAGE(bufoff, gbase, voff) do { _Pragma("unroll") for (int _i = 0; _i < 2; ++_i) \
;         __builtin_amdgcn_global_load_lds((const unsigned*)((const char*)(gbase) + (voff)[_i]), (PG8_LAS unsigned*)(lds + (bufoff) + ldsw + _i * 8192), 16, 0, 0); } while (0)
; #define PG8_LDA(dst, b, h) do { _Pragma("unroll") for (int m = 0; m < 4; ++m) _Pragma("unroll") for (int k = 0; k < 2; ++k) dst[m][k] = *(const PG8_LAS bf16x8*)(lds + PG8_SA(b, h) + aoff + m * 2048 + k * 1024); } while (0)
; #define PG8_LDB(dst, b, h) do { _Pragma("unroll") for (int n = 0; n < 2; ++n) _Pragma("unroll") for (int k = 0; k < 2; ++k) dst[n][k] = *(const PG8_LAS bf16x8*)(lds + PG8_SB(b, h) + boff + n * 2048 + k * 1024); } while (0)
; #define PG8_MMA(ai, bj, At, Bt) do { __builtin_amdgcn_s_setprio(1); _Pragma("unroll") for (int m = 0; m < 4; ++m) _Pragma("unroll") for (int n = 0; n < 2; ++n) _Pragma("unroll") for (int k = 0; k < 2; ++k) \
;         acc[ai][bj][m][n] = __builtin_amdgcn_mfma_f32_16x16x32_bf16(Bt[n][k], At[m][k], acc[ai][bj][m][n], 0, 0, 0); __builtin_amdgcn_s_setprio(0); } while (0)
; #define PG8_WAIT_V(n) asm volatile("s_waitcnt vmcnt(" #n ")" ::: "memory")
; #define PG8_WAIT_L(n) asm volatile("s_waitcnt lgkmcnt(" #n ")" ::: "memory")
; #define PG8_BAR __builtin_amdgcn_s_barrier()
; #define PG8_SCHED __builtin_amdgcn_sched_barrier(0)
; template <class Epi, class Sched, bool ALIGN_EPI = false, bool SP2 = false>
; __device__ __forceinline__ void gemm_phase(PG8_LAS unsigned char* lds, const Gemm g, const Sched& S, const Epi& E) {
;     ...
;             PG8_WAIT_V(8); PG8_WAIT_L(0); PG8_BAR; PG8_MMA(1, 0, At, B0); PG8_MMA(1, 1, At, B1); PG8_BAR; PG8_SCHED;
;             PG8_LDB(B0, 1, 0); PG8_LDB(B1, 1, 1); PG8_SCHED; PG8_LDA(At, 1, 0); PG8_STAGE(PG8_SA(0, 1), a2 + hstep, voffA);
;             PG8_WAIT_V(8); PG8_WAIT_L(0); PG8_BAR; PG8_MMA(0, 0, At, B0); PG8_MMA(0, 1, At, B1); PG8_BAR; PG8_SCHED;
	s_setprio 1
	s_waitcnt lgkmcnt(0)
	v_mfma_f32_16x16x32_bf16 v[62:65], v[130:133], v[162:165], 0
	v_mfma_f32_16x16x32_bf16 v[58:61], v[138:141], v[162:165], 0
	v_mfma_f32_16x16x32_bf16 v[50:53], v[130:133], v[170:173], 0
	v_mfma_f32_16x16x32_bf16 v[42:45], v[138:141], v[170:173], 0
	v_mfma_f32_16x16x32_bf16 v[34:37], v[130:133], v[178:181], 0
	v_mfma_f32_16x16x32_bf16 v[26:29], v[138:141], v[178:181], 0
	v_mfma_f32_16x16x32_bf16 v[18:21], v[130:133], v[186:189], 0
	v_mfma_f32_16x16x32_bf16 v[14:17], v[138:141], v[186:189], 0
	v_mfma_f32_16x16x32_bf16 v[62:65], v[134:137], v[166:169], v[62:65]
	v_mfma_f32_16x16x32_bf16 v[58:61], v[142:145], v[166:169], v[58:61]
	v_mfma_f32_16x16x32_bf16 v[50:53], v[134:137], v[174:177], v[50:53]
	v_mfma_f32_16x16x32_bf16 v[42:45], v[142:145], v[174:177], v[42:45]
	v_mfma_f32_16x16x32_bf16 v[34:37], v[134:137], v[182:185], v[34:37]
	v_mfma_f32_16x16x32_bf16 v[26:29], v[142:145], v[182:185], v[26:29]
	v_mfma_f32_16x16x32_bf16 v[18:21], v[134:137], v[190:193], v[18:21]
	v_mfma_f32_16x16x32_bf16 v[14:17], v[142:145], v[190:193], v[14:17]
	s_setprio 0
	s_setprio 1
	v_mfma_f32_16x16x32_bf16 v[54:57], v[146:149], v[162:165], 0
	v_mfma_f32_16x16x32_bf16 v[46:49], v[154:157], v[162:165], 0
	v_mfma_f32_16x16x32_bf16 v[38:41], v[146:149], v[170:173], 0
	v_mfma_f32_16x16x32_bf16 v[30:33], v[154:157], v[170:173], 0
	v_mfma_f32_16x16x32_bf16 v[22:25], v[146:149], v[178:181], 0
	v_mfma_f32_16x16x32_bf16 v[10:13], v[154:157], v[178:181], 0
	v_mfma_f32_16x16x32_bf16 v[6:9], v[146:149], v[186:189], 0
	v_mfma_f32_16x16x32_bf16 v[2:5], v[154:157], v[186:189], 0
	v_mfma_f32_16x16x32_bf16 v[54:57], v[150:153], v[166:169], v[54:57]
	v_mfma_f32_16x16x32_bf16 v[46:49], v[158:161], v[166:169], v[46:49]
	v_mfma_f32_16x16x32_bf16 v[38:41], v[150:153], v[174:177], v[38:41]
	v_mfma_f32_16x16x32_bf16 v[30:33], v[158:161], v[174:177], v[30:33]
	v_mfma_f32_16x16x32_bf16 v[22:25], v[150:153], v[182:185], v[22:25]
	v_mfma_f32_16x16x32_bf16 v[10:13], v[158:161], v[182:185], v[10:13]
	v_mfma_f32_16x16x32_bf16 v[6:9], v[150:153], v[190:193], v[6:9]
	v_mfma_f32_16x16x32_bf16 v[2:5], v[158:161], v[190:193], v[2:5]
	s_setprio 0
	s_barrier
	s_add_i32 s72, 0, 0x18000
	v_add_u32_e32 v0, s72, v250
	s_add_i32 s73, 0, 0x1c000
	ds_read_b128 v[130:133], v0
	ds_read_b128 v[134:137], v0 offset:1024
	ds_read_b128 v[138:141], v0 offset:2048
	ds_read_b128 v[142:145], v0 offset:3072
	v_add_u32_e32 v0, s73, v250
	ds_read_b128 v[146:149], v0
	ds_read_b128 v[150:153], v0 offset:1024
	ds_read_b128 v[154:157], v0 offset:2048
	ds_read_b128 v[158:161], v0 offset:3072
	s_add_u32 s40, s40, s30
	s_addc_u32 s41, s41, 0
	s_mov_b32 m0, s49
	v_lshl_add_u64 v[222:223], s[40:41], 0, v[198:199]
	ds_read_b128 v[162:165], v252 offset:32768
	ds_read_b128 v[166:169], v252 offset:33792
	ds_read_b128 v[170:173], v252 offset:34816
	ds_read_b128 v[174:177], v252 offset:35840
	ds_read_b128 v[178:181], v252 offset:36864
	ds_read_b128 v[182:185], v252 offset:37888
	ds_read_b128 v[186:189], v252 offset:38912
	ds_read_b128 v[190:193], v252 offset:39936
	global_load_lds_dwordx4 v[222:223], off
	v_lshl_add_u64 v[222:223], s[40:41], 0, v[200:201]
	s_mov_b32 m0, s50
	s_nop 0
	global_load_lds_dwordx4 v[222:223], off
	s_waitcnt vmcnt(8)
	s_waitcnt lgkmcnt(0)
	s_barrier
	s_setprio 1
	s_waitcnt lgkmcnt(0)
	v_mfma_f32_16x16x32_bf16 v[126:129], v[130:133], v[162:165], v[126:129]
	v_mfma_f32_16x16x32_bf16 v[122:125], v[138:141], v[162:165], v[122:125]
	v_mfma_f32_16x16x32_bf16 v[110:113], v[130:133], v[170:173], v[110:113]
	v_mfma_f32_16x16x32_bf16 v[106:109], v[138:141], v[170:173], v[106:109]
	v_mfma_f32_16x16x32_bf16 v[94:97], v[130:133], v[178:181], v[94:97]
	v_mfma_f32_16x16x32_bf16 v[90:93], v[138:141], v[178:181], v[90:93]
	v_mfma_f32_16x16x32_bf16 v[78:81], v[130:133], v[186:189], v[78:81]
	v_mfma_f32_16x16x32_bf16 v[74:77], v[138:141], v[186:189], v[74:77]
	v_mfma_f32_16x16x32_bf16 v[126:129], v[134:137], v[166:169], v[126:129]
	v_mfma_f32_16x16x32_bf16 v[122:125], v[142:145], v[166:169], v[122:125]
	v_mfma_f32_16x16x32_bf16 v[110:113], v[134:137], v[174:177], v[110:113]
	v_mfma_f32_16x16x32_bf16 v[106:109], v[142:145], v[174:177], v[106:109]
	v_mfma_f32_16x16x32_bf16 v[94:97], v[134:137], v[182:185], v[94:97]
	v_mfma_f32_16x16x32_bf16 v[90:93], v[142:145], v[182:185], v[90:93]
	v_mfma_f32_16x16x32_bf16 v[78:81], v[134:137], v[190:193], v[78:81]
	v_mfma_f32_16x16x32_bf16 v[74:77], v[142:145], v[190:193], v[74:77]
	s_setprio 0
	s_setprio 1
	v_mfma_f32_16x16x32_bf16 v[118:121], v[146:149], v[162:165], v[118:121]
	v_mfma_f32_16x16x32_bf16 v[114:117], v[154:157], v[162:165], v[114:117]
	v_mfma_f32_16x16x32_bf16 v[102:105], v[146:149], v[170:173], v[102:105]
	v_mfma_f32_16x16x32_bf16 v[98:101], v[154:157], v[170:173], v[98:101]
	v_mfma_f32_16x16x32_bf16 v[86:89], v[146:149], v[178:181], v[86:89]
	v_mfma_f32_16x16x32_bf16 v[82:85], v[154:157], v[178:181], v[82:85]
	v_mfma_f32_16x16x32_bf16 v[70:73], v[146:149], v[186:189], v[70:73]
	v_mfma_f32_16x16x32_bf16 v[66:69], v[154:157], v[186:189], v[66:69]
	v_mfma_f32_16x16x32_bf16 v[118:121], v[150:153], v[166:169], v[118:121]
	v_mfma_f32_16x16x32_bf16 v[114:117], v[158:161], v[166:169], v[114:117]
	v_mfma_f32_16x16x32_bf16 v[102:105], v[150:153], v[174:177], v[102:105]
	v_mfma_f32_16x16x32_bf16 v[98:101], v[158:161], v[174:177], v[98:101]
	v_mfma_f32_16x16x32_bf16 v[86:89], v[150:153], v[182:185], v[86:89]
	v_mfma_f32_16x16x32_bf16 v[82:85], v[158:161], v[182:185], v[82:85]
	v_mfma_f32_16x16x32_bf16 v[70:73], v[150:153], v[190:193], v[70:73]
	v_mfma_f32_16x16x32_bf16 v[66:69], v[158:161], v[190:193], v[66:69]
	s_setprio 0
	s_barrier
; #define PG8_STAGE(bufoff, gbase, voff) do { _Pragma("unroll") for (int _i = 0; _i < 2; ++_i) \
;         __builtin_amdgcn_global_load_lds((const unsigned*)((const char*)(gbase) + (voff)[_i]), (PG8_LAS unsigned*)(lds + (bufoff) + ldsw + _i * 8192), 16, 0, 0); } while (0)
; #define PG8_LDA(dst, b, h) do { _Pragma("unroll") for (int m = 0; m < 4; ++m) _Pragma("unroll") for (int k = 0; k < 2; ++k) dst[m][k] = *(const PG8_LAS bf16x8*)(lds + PG8_SA(b, h) + aoff + m * 2048 + k * 1024); } while (0)
; #define PG8_MMA(ai, bj, At, Bt) do { __builtin_amdgcn_s_setprio(1); _Pragma("unroll") for (int m = 0; m < 4; ++m) _Pragma("unroll") for (int n = 0; n < 2; ++n) _Pragma("unroll") for (int k = 0; k < 2; ++k) \
;         acc[ai][bj][m][n] = __builtin_amdgcn_mfma_f32_16x16x32_bf16(Bt[n][k], At[m][k], acc[ai][bj][m][n], 0, 0, 0); __builtin_amdgcn_s_setprio(0); } while (0)
; #define PG8_WAIT_V(n) asm volatile("s_waitcnt vmcnt(" #n ")" ::: "memory")
; #define PG8_WAIT_L(n) asm volatile("s_waitcnt lgkmcnt(" #n ")" ::: "memory")
; #define PG8_BAR __builtin_amdgcn_s_barrier()
; #define PG8_SCHED __builtin_amdgcn_sched_barrier(0)
; template <class Epi, class Sched, bool ALIGN_EPI = false, bool SP2 = false>
; __device__ __forceinline__ void gemm_phase(PG8_LAS unsigned char* lds, const Gemm g, const Sched& S, const Epi& E) {
;     ...
;             PG8_LDA(At, 1, 1); PG8_STAGE(PG8_SB(1, 0), b3, voffB); PG8_STAGE(PG8_SB(1, 1), b3 + hstep, voffB); PG8_STAGE(PG8_SA(1, 0), a3, voffA);
;             PG8_WAIT_V(8); PG8_WAIT_L(0); PG8_BAR; PG8_MMA(1, 0, At, B0); PG8_MMA(1, 1, At, B1); PG8_BAR; PG8_SCHED;
	s_add_i32 s40, s72, s44
	v_lshl_add_u64 v[210:211], v[210:211], 0, s[58:59]
	s_mov_b32 m0, s40
	ds_read_b128 v[162:165], v252 offset:49152
	ds_read_b128 v[166:169], v252 offset:50176
	ds_read_b128 v[170:173], v252 offset:51200
	ds_read_b128 v[174:177], v252 offset:52224
	ds_read_b128 v[178:181], v252 offset:53248
	ds_read_b128 v[182:185], v252 offset:54272
	ds_read_b128 v[186:189], v252 offset:55296
	ds_read_b128 v[190:193], v252 offset:56320
	global_load_lds_dwordx4 v[210:211], off
	v_lshl_add_u64 v[210:211], v[212:213], 0, s[58:59]
	s_add_i32 m0, s40, 0x2000
	s_add_i32 s40, s73, s44
	global_load_lds_dwordx4 v[210:211], off
	v_lshl_add_u64 v[210:211], v[214:215], 0, s[58:59]
	s_mov_b32 m0, s40
	s_nop 0
	global_load_lds_dwordx4 v[210:211], off
	v_lshl_add_u64 v[210:211], v[216:217], 0, s[58:59]
	s_add_i32 m0, s40, 0x2000
	s_nop 0
	global_load_lds_dwordx4 v[210:211], off
	v_lshl_add_u64 v[210:211], v[218:219], 0, s[58:59]
	s_mov_b32 m0, s55
	s_nop 0
	global_load_lds_dwordx4 v[210:211], off
	v_lshl_add_u64 v[210:211], v[220:221], 0, s[58:59]
	s_mov_b32 m0, s63
	s_nop 0
	global_load_lds_dwordx4 v[210:211], off
	s_waitcnt vmcnt(8)
	s_waitcnt lgkmcnt(0)
	s_barrier
	s_setprio 1
	s_waitcnt lgkmcnt(0)
	v_mfma_f32_16x16x32_bf16 v[62:65], v[130:133], v[162:165], v[62:65]
	v_mfma_f32_16x16x32_bf16 v[58:61], v[138:141], v[162:165], v[58:61]
	v_mfma_f32_16x16x32_bf16 v[50:53], v[130:133], v[170:173], v[50:53]
	v_mfma_f32_16x16x32_bf16 v[42:45], v[138:141], v[170:173], v[42:45]
	v_mfma_f32_16x16x32_bf16 v[34:37], v[130:133], v[178:181], v[34:37]
	v_mfma_f32_16x16x32_bf16 v[26:29], v[138:141], v[178:181], v[26:29]
	v_mfma_f32_16x16x32_bf16 v[18:21], v[130:133], v[186:189], v[18:21]
	v_mfma_f32_16x16x32_bf16 v[14:17], v[138:141], v[186:189], v[14:17]
	v_mfma_f32_16x16x32_bf16 v[62:65], v[134:137], v[166:169], v[62:65]
	v_mfma_f32_16x16x32_bf16 v[58:61], v[142:145], v[166:169], v[58:61]
	v_mfma_f32_16x16x32_bf16 v[50:53], v[134:137], v[174:177], v[50:53]
	v_mfma_f32_16x16x32_bf16 v[42:45], v[142:145], v[174:177], v[42:45]
	v_mfma_f32_16x16x32_bf16 v[34:37], v[134:137], v[182:185], v[34:37]
	v_mfma_f32_16x16x32_bf16 v[26:29], v[142:145], v[182:185], v[26:29]
	v_mfma_f32_16x16x32_bf16 v[18:21], v[134:137], v[190:193], v[18:21]
	v_mfma_f32_16x16x32_bf16 v[14:17], v[142:145], v[190:193], v[14:17]
	s_setprio 0
	s_setprio 1
	v_mfma_f32_16x16x32_bf16 v[54:57], v[146:149], v[162:165], v[54:57]
	v_mfma_f32_16x16x32_bf16 v[46:49], v[154:157], v[162:165], v[46:49]
	v_mfma_f32_16x16x32_bf16 v[38:41], v[146:149], v[170:173], v[38:41]
	v_mfma_f32_16x16x32_bf16 v[30:33], v[154:157], v[170:173], v[30:33]
	v_mfma_f32_16x16x32_bf16 v[22:25], v[146:149], v[178:181], v[22:25]
	v_mfma_f32_16x16x32_bf16 v[10:13], v[154:157], v[178:181], v[10:13]
	v_mfma_f32_16x16x32_bf16 v[6:9], v[146:149], v[186:189], v[6:9]
	v_mfma_f32_16x16x32_bf16 v[2:5], v[154:157], v[186:189], v[2:5]
	v_mfma_f32_16x16x32_bf16 v[54:57], v[150:153], v[166:169], v[54:57]
	v_mfma_f32_16x16x32_bf16 v[46:49], v[158:161], v[166:169], v[46:49]
	v_mfma_f32_16x16x32_bf16 v[38:41], v[150:153], v[174:177], v[38:41]
	v_mfma_f32_16x16x32_bf16 v[30:33], v[158:161], v[174:177], v[30:33]
	v_mfma_f32_16x16x32_bf16 v[22:25], v[150:153], v[182:185], v[22:25]
	v_mfma_f32_16x16x32_bf16 v[10:13], v[158:161], v[182:185], v[10:13]
	v_mfma_f32_16x16x32_bf16 v[6:9], v[150:153], v[190:193], v[6:9]
	v_mfma_f32_16x16x32_bf16 v[2:5], v[158:161], v[190:193], v[2:5]
	s_setprio 0
	s_barrier
	s_add_u32 s38, s38, 0x100
	s_addc_u32 s39, s39, 0
	s_add_u32 s86, s86, 0x100
	s_addc_u32 s87, s87, 0
	s_cmp_ge_u32 vcc_lo, s93
	s_mov_b32 s40, vcc_lo
	s_cbranch_scc1 .Lpeel_done_807

;     __device__ __forceinline__ void operator()(const f32x4 (&acc)[2][2][4][2], const Unit& u, int wr, int wc, int fr, int fq) const {
;         const int row0 = u.pm * BM + wr * 64 + fr, col0 = u.pn * BM + wc * 32 + 4 * fq;
;         const int mr = u.pm < 64 ? (u.pm >> 3) : 8;
;         f32x4 gv[2][2];
; #pragma unroll
;         for (int bj = 0; bj < 2; ++bj)
; #pragma unroll
;             for (int n = 0; n < 2; ++n) gv[bj][n] = *(const f32x4*)(gate + (size_t)mr * 9216 + col0 + bj * HALF + n * 16) * s;
.Lpeel_done_807:
	s_cmp_gt_i32 s28, 63
	s_mov_b64 s[38:39], 0x12000
	s_cbranch_scc1 .LBB0_810
	s_ashr_i32 s38, s28, 3
	s_mul_hi_i32 s39, s38, 0x2400
	s_mulk_i32 s38, 0x2400

; #define PG8_STAGE(bufoff, gbase, voff) do { _Pragma("unroll") for (int _i = 0; _i < 2; ++_i) \
;         __builtin_amdgcn_global_load_lds((const unsigned*)((const char*)(gbase) + (voff)[_i]), (PG8_LAS unsigned*)(lds + (bufoff) + ldsw + _i * 8192), 16, 0, 0); } while (0)
; #define PG8_LDA(dst, b, h) do { _Pragma("unroll") for (int m = 0; m < 4; ++m) _Pragma("unroll") for (int k = 0; k < 2; ++k) dst[m][k] = *(const PG8_LAS bf16x8*)(lds + PG8_SA(b, h) + aoff + m * 2048 + k * 1024); } while (0)
; #define PG8_LDB(dst, b, h) do { _Pragma("unroll") for (int n = 0; n < 2; ++n) _Pragma("unroll") for (int k = 0; k < 2; ++k) dst[n][k] = *(const PG8_LAS bf16x8*)(lds + PG8_SB(b, h) + boff + n * 2048 + k * 1024); } while (0)
; #define PG8_MMA(ai, bj, At, Bt) do { __builtin_amdgcn_s_setprio(1); _Pragma("unroll") for (int m = 0; m < 4; ++m) _Pragma("unroll") for (int n = 0; n < 2; ++n) _Pragma("unroll") for (int k = 0; k < 2; ++k) \
;         acc[ai][bj][m][n] = __builtin_amdgcn_mfma_f32_16x16x32_bf16(Bt[n][k], At[m][k], acc[ai][bj][m][n], 0, 0, 0); __builtin_amdgcn_s_setprio(0); } while (0)
; #define PG8_WAIT_V(n) asm volatile("s_waitcnt vmcnt(" #n ")" ::: "memory")
; #define PG8_WAIT_L(n) asm volatile("s_waitcnt lgkmcnt(" #n ")" ::: "memory")
; #define PG8_BAR __builtin_amdgcn_s_barrier()
; #define PG8_SCHED __builtin_amdgcn_sched_barrier(0)
; template <class Epi, class Sched, bool ALIGN_EPI = false, bool SP2 = false>
; __device__ __forceinline__ void gemm_phase(PG8_LAS unsigned char* lds, const Gemm g, const Sched& S, const Epi& E) {
;     ...
;             PG8_LDB(B0, 0, 0); PG8_LDB(B1, 0, 1); PG8_SCHED; PG8_LDA(At, 0, 0); PG8_STAGE(PG8_SA(1, 1), a1 + hstep, voffA);
;             PG8_WAIT_V(8); PG8_WAIT_L(0); PG8_BAR; PG8_MMA(0, 0, At, B0); PG8_MMA(0, 1, At, B1); PG8_BAR; PG8_SCHED;
;             PG8_LDA(At, 0, 1); PG8_STAGE(PG8_SB(0, 0), b2, voffB); PG8_STAGE(PG8_SB(0, 1), b2 + hstep, voffB); PG8_STAGE(PG8_SA(0, 0), a2, voffA);
;             PG8_WAIT_V(8); PG8_WAIT_L(0); PG8_BAR; PG8_MMA(1, 0, At, B0); PG8_MMA(1, 1, At, B1); PG8_BAR; PG8_SCHED;
.LBB0_832:
	s_add_u32 s30, s30, 0x80
	s_addc_u32 s31, s31, 0
	s_add_u32 s65, s38, 0x100
	s_addc_u32 s86, s39, 0
	s_mov_b32 s38, 0
	s_add_i32 s87, s38, 2
	s_add_u32 s72, s30, 0x80
	s_addc_u32 s39, s31, 0
	s_add_i32 s78, 0, 0x10000
	s_cmp_eq_u32 s54, s38
	s_cselect_b32 s39, s21, s39
	s_cselect_b32 s38, s20, s72
	v_add_u32_e32 v0, s78, v139
	s_cselect_b32 s73, s7, s86
	s_cselect_b32 s72, s6, s65
	s_add_i32 s79, 0, 0x14000
	ds_read_b128 v[142:145], v0
	ds_read_b128 v[146:149], v0 offset:1024
	ds_read_b128 v[150:153], v0 offset:2048
	ds_read_b128 v[154:157], v0 offset:3072
	v_add_u32_e32 v0, s79, v139
	ds_read_b128 v[158:161], v0
	ds_read_b128 v[162:165], v0 offset:1024
	ds_read_b128 v[166:169], v0 offset:2048
	ds_read_b128 v[170:173], v0 offset:3072
	v_lshl_add_u64 v[210:211], s[30:31], 0, v[134:135]
	s_add_i32 m0, s42, 0xc000
	ds_read_b128 v[174:177], v141
	ds_read_b128 v[178:181], v141 offset:1024
	ds_read_b128 v[182:185], v141 offset:2048
	ds_read_b128 v[186:189], v141 offset:3072
	ds_read_b128 v[190:193], v141 offset:4096
	ds_read_b128 v[198:201], v141 offset:5120
	ds_read_b128 v[202:205], v141 offset:6144
	ds_read_b128 v[206:209], v141 offset:7168
	global_load_lds_dwordx4 v[210:211], off
	v_lshl_add_u64 v[210:211], s[30:31], 0, v[136:137]
	s_add_i32 m0, s42, 0xe000
	s_nop 0
	global_load_lds_dwordx4 v[210:211], off
	s_waitcnt vmcnt(8)
	s_waitcnt lgkmcnt(0)
	s_barrier
	s_setprio 1
	s_waitcnt lgkmcnt(0)
	v_mfma_f32_16x16x32_bf16 v[126:129], v[142:145], v[174:177], 0
	v_mfma_f32_16x16x32_bf16 v[122:125], v[150:153], v[174:177], 0
	v_mfma_f32_16x16x32_bf16 v[118:121], v[142:145], v[182:185], 0
	v_mfma_f32_16x16x32_bf16 v[114:117], v[150:153], v[182:185], 0
	v_mfma_f32_16x16x32_bf16 v[110:113], v[142:145], v[190:193], 0
	v_mfma_f32_16x16x32_bf16 v[102:105], v[150:153], v[190:193], 0
	v_mfma_f32_16x16x32_bf16 v[90:93], v[142:145], v[202:205], 0
	v_mfma_f32_16x16x32_bf16 v[82:85], v[150:153], v[202:205], 0
	v_mfma_f32_16x16x32_bf16 v[126:129], v[146:149], v[178:181], v[126:129]
	v_mfma_f32_16x16x32_bf16 v[122:125], v[154:157], v[178:181], v[122:125]
	v_mfma_f32_16x16x32_bf16 v[118:121], v[146:149], v[186:189], v[118:121]
	v_mfma_f32_16x16x32_bf16 v[114:117], v[154:157], v[186:189], v[114:117]
	v_mfma_f32_16x16x32_bf16 v[110:113], v[146:149], v[198:201], v[110:113]
	v_mfma_f32_16x16x32_bf16 v[102:105], v[154:157], v[198:201], v[102:105]
	v_mfma_f32_16x16x32_bf16 v[90:93], v[146:149], v[206:209], v[90:93]
	v_mfma_f32_16x16x32_bf16 v[82:85], v[154:157], v[206:209], v[82:85]
	s_setprio 0
	s_setprio 1
	v_mfma_f32_16x16x32_bf16 v[106:109], v[158:161], v[174:177], 0
	v_mfma_f32_16x16x32_bf16 v[98:101], v[166:169], v[174:177], 0
	v_mfma_f32_16x16x32_bf16 v[94:97], v[158:161], v[182:185], 0
	v_mfma_f32_16x16x32_bf16 v[86:89], v[166:169], v[182:185], 0
	v_mfma_f32_16x16x32_bf16 v[78:81], v[158:161], v[190:193], 0
	v_mfma_f32_16x16x32_bf16 v[74:77], v[166:169], v[190:193], 0
	v_mfma_f32_16x16x32_bf16 v[70:73], v[158:161], v[202:205], 0
	v_mfma_f32_16x16x32_bf16 v[66:69], v[166:169], v[202:205], 0
	v_mfma_f32_16x16x32_bf16 v[106:109], v[162:165], v[178:181], v[106:109]
	v_mfma_f32_16x16x32_bf16 v[98:101], v[170:173], v[178:181], v[98:101]
	v_mfma_f32_16x16x32_bf16 v[94:97], v[162:165], v[186:189], v[94:97]
	v_mfma_f32_16x16x32_bf16 v[86:89], v[170:173], v[186:189], v[86:89]
	v_mfma_f32_16x16x32_bf16 v[78:81], v[162:165], v[198:201], v[78:81]
	v_mfma_f32_16x16x32_bf16 v[74:77], v[170:173], v[198:201], v[74:77]
	v_mfma_f32_16x16x32_bf16 v[70:73], v[162:165], v[206:209], v[70:73]
	v_mfma_f32_16x16x32_bf16 v[66:69], v[170:173], v[206:209], v[66:69]
	s_setprio 0
	s_barrier
	s_add_i32 s78, s78, s41
	v_lshl_add_u64 v[210:211], s[72:73], 0, v[132:133]
	s_mov_b32 m0, s78
	ds_read_b128 v[174:177], v141 offset:16384
	ds_read_b128 v[178:181], v141 offset:17408
	ds_read_b128 v[182:185], v141 offset:18432
	ds_read_b128 v[186:189], v141 offset:19456
	ds_read_b128 v[190:193], v141 offset:20480
	ds_read_b128 v[198:201], v141 offset:21504
	ds_read_b128 v[202:205], v141 offset:22528
	ds_read_b128 v[206:209], v141 offset:23552
	global_load_lds_dwordx4 v[210:211], off
	s_add_i32 m0, s78, 0x2000
	v_lshl_add_u64 v[212:213], s[72:73], 0, v[130:131]
	s_add_u32 s72, s72, s8
	s_addc_u32 s73, s73, 0
	s_add_i32 s78, s79, s41
	global_load_lds_dwordx4 v[212:213], off
	v_lshl_add_u64 v[214:215], s[72:73], 0, v[132:133]
	s_mov_b32 m0, s78
	v_lshl_add_u64 v[216:217], s[72:73], 0, v[130:131]
	global_load_lds_dwordx4 v[214:215], off
	s_add_i32 m0, s78, 0x2000
	v_lshl_add_u64 v[218:219], s[38:39], 0, v[132:133]
	global_load_lds_dwordx4 v[216:217], off
	s_mov_b32 m0, s42
	v_lshl_add_u64 v[220:221], s[38:39], 0, v[130:131]
	global_load_lds_dwordx4 v[218:219], off
	s_mov_b32 m0, s43
	s_nop 0
	global_load_lds_dwordx4 v[220:221], off
	s_waitcnt vmcnt(8)
	s_waitcnt lgkmcnt(0)
	s_barrier
; #define PG8_STAGE(bufoff, gbase, voff) do { _Pragma("unroll") for (int _i = 0; _i < 2; ++_i) \
;         __builtin_amdgcn_global_load_lds((const unsigned*)((const char*)(gbase) + (voff)[_i]), (PG8_LAS unsigned*)(lds + (bufoff) + ldsw + _i * 8192), 16, 0, 0); } while (0)
; #define PG8_LDA(dst, b, h) do { _Pragma("unroll") for (int m = 0; m < 4; ++m) _Pragma("unroll") for (int k = 0; k < 2; ++k) dst[m][k] = *(const PG8_LAS bf16x8*)(lds + PG8_SA(b, h) + aoff + m * 2048 + k * 1024); } while (0)
; #define PG8_LDB(dst, b, h) do { _Pragma("unroll") for (int n = 0; n < 2; ++n) _Pragma("unroll") for (int k = 0; k < 2; ++k) dst[n][k] = *(const PG8_LAS bf16x8*)(lds + PG8_SB(b, h) + boff + n * 2048 + k * 1024); } while (0)
; #define PG8_MMA(ai, bj, At, Bt) do { __builtin_amdgcn_s_setprio(1); _Pragma("unroll") for (int m = 0; m < 4; ++m) _Pragma("unroll") for (int n = 0; n < 2; ++n) _Pragma("unroll") for (int k = 0; k < 2; ++k) \
;         acc[ai][bj][m][n] = __builtin_amdgcn_mfma_f32_16x16x32_bf16(Bt[n][k], At[m][k], acc[ai][bj][m][n], 0, 0, 0); __builtin_amdgcn_s_setprio(0); } while (0)
; #define PG8_WAIT_V(n) asm volatile("s_waitcnt vmcnt(" #n ")" ::: "memory")
; #define PG8_WAIT_L(n) asm volatile("s_waitcnt lgkmcnt(" #n ")" ::: "memory")
; #define PG8_BAR __builtin_amdgcn_s_barrier()
; #define PG8_SCHED __builtin_amdgcn_sched_barrier(0)
; template <class Epi, class Sched, bool ALIGN_EPI = false, bool SP2 = false>
; __device__ __forceinline__ void gemm_phase(PG8_LAS unsigned char* lds, const Gemm g, const Sched& S, const Epi& E) {
;     ...
;             PG8_WAIT_V(8); PG8_WAIT_L(0); PG8_BAR; PG8_MMA(1, 0, At, B0); PG8_MMA(1, 1, At, B1); PG8_BAR; PG8_SCHED;
;             PG8_LDB(B0, 1, 0); PG8_LDB(B1, 1, 1); PG8_SCHED; PG8_LDA(At, 1, 0); PG8_STAGE(PG8_SA(0, 1), a2 + hstep, voffA);
;             PG8_WAIT_V(8); PG8_WAIT_L(0); PG8_BAR; PG8_MMA(0, 0, At, B0); PG8_MMA(0, 1, At, B1); PG8_BAR; PG8_SCHED;
	s_setprio 1
	s_waitcnt lgkmcnt(0)
	v_mfma_f32_16x16x32_bf16 v[62:65], v[142:145], v[174:177], 0
	v_mfma_f32_16x16x32_bf16 v[58:61], v[150:153], v[174:177], 0
	v_mfma_f32_16x16x32_bf16 v[54:57], v[142:145], v[182:185], 0
	v_mfma_f32_16x16x32_bf16 v[50:53], v[150:153], v[182:185], 0
	v_mfma_f32_16x16x32_bf16 v[42:45], v[142:145], v[190:193], 0
	v_mfma_f32_16x16x32_bf16 v[34:37], v[150:153], v[190:193], 0
	v_mfma_f32_16x16x32_bf16 v[26:29], v[142:145], v[202:205], 0
	v_mfma_f32_16x16x32_bf16 v[18:21], v[150:153], v[202:205], 0
	v_mfma_f32_16x16x32_bf16 v[62:65], v[146:149], v[178:181], v[62:65]
	v_mfma_f32_16x16x32_bf16 v[58:61], v[154:157], v[178:181], v[58:61]
	v_mfma_f32_16x16x32_bf16 v[54:57], v[146:149], v[186:189], v[54:57]
	v_mfma_f32_16x16x32_bf16 v[50:53], v[154:157], v[186:189], v[50:53]
	v_mfma_f32_16x16x32_bf16 v[42:45], v[146:149], v[198:201], v[42:45]
	v_mfma_f32_16x16x32_bf16 v[34:37], v[154:157], v[198:201], v[34:37]
	v_mfma_f32_16x16x32_bf16 v[26:29], v[146:149], v[206:209], v[26:29]
	v_mfma_f32_16x16x32_bf16 v[18:21], v[154:157], v[206:209], v[18:21]
	s_setprio 0
	s_setprio 1
	v_mfma_f32_16x16x32_bf16 v[46:49], v[158:161], v[174:177], 0
	v_mfma_f32_16x16x32_bf16 v[38:41], v[166:169], v[174:177], 0
	v_mfma_f32_16x16x32_bf16 v[30:33], v[158:161], v[182:185], 0
	v_mfma_f32_16x16x32_bf16 v[22:25], v[166:169], v[182:185], 0
	v_mfma_f32_16x16x32_bf16 v[14:17], v[158:161], v[190:193], 0
	v_mfma_f32_16x16x32_bf16 v[10:13], v[166:169], v[190:193], 0
	v_mfma_f32_16x16x32_bf16 v[6:9], v[158:161], v[202:205], 0
	v_mfma_f32_16x16x32_bf16 v[2:5], v[166:169], v[202:205], 0
	v_mfma_f32_16x16x32_bf16 v[46:49], v[162:165], v[178:181], v[46:49]
	v_mfma_f32_16x16x32_bf16 v[38:41], v[170:173], v[178:181], v[38:41]
	v_mfma_f32_16x16x32_bf16 v[30:33], v[162:165], v[186:189], v[30:33]
	v_mfma_f32_16x16x32_bf16 v[22:25], v[170:173], v[186:189], v[22:25]
	v_mfma_f32_16x16x32_bf16 v[14:17], v[162:165], v[198:201], v[14:17]
	v_mfma_f32_16x16x32_bf16 v[10:13], v[170:173], v[198:201], v[10:13]
	v_mfma_f32_16x16x32_bf16 v[6:9], v[162:165], v[206:209], v[6:9]
	v_mfma_f32_16x16x32_bf16 v[2:5], v[170:173], v[206:209], v[2:5]
	s_setprio 0
	s_barrier
	s_add_i32 s72, 0, 0x18000
	v_add_u32_e32 v0, s72, v139
	s_add_i32 s73, 0, 0x1c000
	ds_read_b128 v[142:145], v0
	ds_read_b128 v[146:149], v0 offset:1024
	ds_read_b128 v[150:153], v0 offset:2048
	ds_read_b128 v[154:157], v0 offset:3072
	v_add_u32_e32 v0, s73, v139
	ds_read_b128 v[158:161], v0
	ds_read_b128 v[162:165], v0 offset:1024
	ds_read_b128 v[166:169], v0 offset:2048
	ds_read_b128 v[170:173], v0 offset:3072
	s_add_u32 s38, s38, s8
	s_addc_u32 s39, s39, 0
	s_mov_b32 m0, s44
	v_lshl_add_u64 v[222:223], s[38:39], 0, v[132:133]
	ds_read_b128 v[174:177], v141 offset:32768
	ds_read_b128 v[178:181], v141 offset:33792
	ds_read_b128 v[182:185], v141 offset:34816
	ds_read_b128 v[186:189], v141 offset:35840
	ds_read_b128 v[190:193], v141 offset:36864
	ds_read_b128 v[198:201], v141 offset:37888
	ds_read_b128 v[202:205], v141 offset:38912
	ds_read_b128 v[206:209], v141 offset:39936
	global_load_lds_dwordx4 v[222:223], off
	v_lshl_add_u64 v[222:223], s[38:39], 0, v[130:131]
	s_mov_b32 m0, s45
	s_nop 0
	global_load_lds_dwordx4 v[222:223], off
	s_waitcnt vmcnt(8)
	s_waitcnt lgkmcnt(0)
	s_barrier
	s_setprio 1
	s_waitcnt lgkmcnt(0)
	v_mfma_f32_16x16x32_bf16 v[126:129], v[142:145], v[174:177], v[126:129]
	v_mfma_f32_16x16x32_bf16 v[122:125], v[150:153], v[174:177], v[122:125]
	v_mfma_f32_16x16x32_bf16 v[118:121], v[142:145], v[182:185], v[118:121]
	v_mfma_f32_16x16x32_bf16 v[114:117], v[150:153], v[182:185], v[114:117]
	v_mfma_f32_16x16x32_bf16 v[110:113], v[142:145], v[190:193], v[110:113]
	v_mfma_f32_16x16x32_bf16 v[102:105], v[150:153], v[190:193], v[102:105]
	v_mfma_f32_16x16x32_bf16 v[90:93], v[142:145], v[202:205], v[90:93]
	v_mfma_f32_16x16x32_bf16 v[82:85], v[150:153], v[202:205], v[82:85]
	v_mfma_f32_16x16x32_bf16 v[126:129], v[146:149], v[178:181], v[126:129]
	v_mfma_f32_16x16x32_bf16 v[122:125], v[154:157], v[178:181], v[122:125]
	v_mfma_f32_16x16x32_bf16 v[118:121], v[146:149], v[186:189], v[118:121]
	v_mfma_f32_16x16x32_bf16 v[114:117], v[154:157], v[186:189], v[114:117]
	v_mfma_f32_16x16x32_bf16 v[110:113], v[146:149], v[198:201], v[110:113]
	v_mfma_f32_16x16x32_bf16 v[102:105], v[154:157], v[198:201], v[102:105]
	v_mfma_f32_16x16x32_bf16 v[90:93], v[146:149], v[206:209], v[90:93]
	v_mfma_f32_16x16x32_bf16 v[82:85], v[154:157], v[206:209], v[82:85]
	s_setprio 0
	s_setprio 1
	v_mfma_f32_16x16x32_bf16 v[106:109], v[158:161], v[174:177], v[106:109]
	v_mfma_f32_16x16x32_bf16 v[98:101], v[166:169], v[174:177], v[98:101]
	v_mfma_f32_16x16x32_bf16 v[94:97], v[158:161], v[182:185], v[94:97]
	v_mfma_f32_16x16x32_bf16 v[86:89], v[166:169], v[182:185], v[86:89]
	v_mfma_f32_16x16x32_bf16 v[78:81], v[158:161], v[190:193], v[78:81]
	v_mfma_f32_16x16x32_bf16 v[74:77], v[166:169], v[190:193], v[74:77]
	v_mfma_f32_16x16x32_bf16 v[70:73], v[158:161], v[202:205], v[70:73]
	v_mfma_f32_16x16x32_bf16 v[66:69], v[166:169], v[202:205], v[66:69]
	v_mfma_f32_16x16x32_bf16 v[106:109], v[162:165], v[178:181], v[106:109]
	v_mfma_f32_16x16x32_bf16 v[98:101], v[170:173], v[178:181], v[98:101]
	v_mfma_f32_16x16x32_bf16 v[94:97], v[162:165], v[186:189], v[94:97]
	v_mfma_f32_16x16x32_bf16 v[86:89], v[170:173], v[186:189], v[86:89]
	v_mfma_f32_16x16x32_bf16 v[78:81], v[162:165], v[198:201], v[78:81]
	v_mfma_f32_16x16x32_bf16 v[74:77], v[170:173], v[198:201], v[74:77]
	v_mfma_f32_16x16x32_bf16 v[70:73], v[162:165], v[206:209], v[70:73]
	v_mfma_f32_16x16x32_bf16 v[66:69], v[170:173], v[206:209], v[66:69]
	s_setprio 0
	s_barrier
; #define PG8_STAGE(bufoff, gbase, voff) do { _Pragma("unroll") for (int _i = 0; _i < 2; ++_i) \
;         __builtin_amdgcn_global_load_lds((const unsigned*)((const char*)(gbase) + (voff)[_i]), (PG8_LAS unsigned*)(lds + (bufoff) + ldsw + _i * 8192), 16, 0, 0); } while (0)
; #define PG8_LDA(dst, b, h) do { _Pragma("unroll") for (int m = 0; m < 4; ++m) _Pragma("unroll") for (int k = 0; k < 2; ++k) dst[m][k] = *(const PG8_LAS bf16x8*)(lds + PG8_SA(b, h) + aoff + m * 2048 + k * 1024); } while (0)
; #define PG8_MMA(ai, bj, At, Bt) do { __builtin_amdgcn_s_setprio(1); _Pragma("unroll") for (int m = 0; m < 4; ++m) _Pragma("unroll") for (int n = 0; n < 2; ++n) _Pragma("unroll") for (int k = 0; k < 2; ++k) \
;         acc[ai][bj][m][n] = __builtin_amdgcn_mfma_f32_16x16x32_bf16(Bt[n][k], At[m][k], acc[ai][bj][m][n], 0, 0, 0); __builtin_amdgcn_s_setprio(0); } while (0)
; #define PG8_WAIT_V(n) asm volatile("s_waitcnt vmcnt(" #n ")" ::: "memory")
; #define PG8_WAIT_L(n) asm volatile("s_waitcnt lgkmcnt(" #n ")" ::: "memory")
; #define PG8_BAR __builtin_amdgcn_s_barrier()
; #define PG8_SCHED __builtin_amdgcn_sched_barrier(0)
; template <class Epi, class Sched, bool ALIGN_EPI = false, bool SP2 = false>
; __device__ __forceinline__ void gemm_phase(PG8_LAS unsigned char* lds, const Gemm g, const Sched& S, const Epi& E) {
;     ...
;             PG8_LDA(At, 1, 1); PG8_STAGE(PG8_SB(1, 0), b3, voffB); PG8_STAGE(PG8_SB(1, 1), b3 + hstep, voffB); PG8_STAGE(PG8_SA(1, 0), a3, voffA);
;             PG8_WAIT_V(8); PG8_WAIT_L(0); PG8_BAR; PG8_MMA(1, 0, At, B0); PG8_MMA(1, 1, At, B1); PG8_BAR; PG8_SCHED;
	s_add_i32 s38, s72, s41
	v_lshl_add_u64 v[210:211], v[210:211], 0, s[58:59]
	s_mov_b32 m0, s38
	ds_read_b128 v[174:177], v141 offset:49152
	ds_read_b128 v[178:181], v141 offset:50176
	ds_read_b128 v[182:185], v141 offset:51200
	ds_read_b128 v[186:189], v141 offset:52224
	ds_read_b128 v[190:193], v141 offset:53248
	ds_read_b128 v[198:201], v141 offset:54272
	ds_read_b128 v[202:205], v141 offset:55296
	ds_read_b128 v[206:209], v141 offset:56320
	global_load_lds_dwordx4 v[210:211], off
	v_lshl_add_u64 v[210:211], v[212:213], 0, s[58:59]
	s_add_i32 m0, s38, 0x2000
	s_add_i32 s38, s73, s41
	global_load_lds_dwordx4 v[210:211], off
	v_lshl_add_u64 v[210:211], v[214:215], 0, s[58:59]
	s_mov_b32 m0, s38
	s_nop 0
	global_load_lds_dwordx4 v[210:211], off
	v_lshl_add_u64 v[210:211], v[216:217], 0, s[58:59]
	s_add_i32 m0, s38, 0x2000
	s_nop 0
	global_load_lds_dwordx4 v[210:211], off
	v_lshl_add_u64 v[210:211], v[218:219], 0, s[58:59]
	s_mov_b32 m0, s50
	s_nop 0
	global_load_lds_dwordx4 v[210:211], off
	v_lshl_add_u64 v[210:211], v[220:221], 0, s[58:59]
	s_mov_b32 m0, s51
	s_nop 0
	global_load_lds_dwordx4 v[210:211], off
	s_waitcnt vmcnt(8)
	s_waitcnt lgkmcnt(0)
	s_barrier
	s_setprio 1
	s_waitcnt lgkmcnt(0)
	v_mfma_f32_16x16x32_bf16 v[62:65], v[142:145], v[174:177], v[62:65]
	v_mfma_f32_16x16x32_bf16 v[58:61], v[150:153], v[174:177], v[58:61]
	v_mfma_f32_16x16x32_bf16 v[54:57], v[142:145], v[182:185], v[54:57]
	v_mfma_f32_16x16x32_bf16 v[50:53], v[150:153], v[182:185], v[50:53]
	v_mfma_f32_16x16x32_bf16 v[42:45], v[142:145], v[190:193], v[42:45]
	v_mfma_f32_16x16x32_bf16 v[34:37], v[150:153], v[190:193], v[34:37]
	v_mfma_f32_16x16x32_bf16 v[26:29], v[142:145], v[202:205], v[26:29]
	v_mfma_f32_16x16x32_bf16 v[18:21], v[150:153], v[202:205], v[18:21]
	v_mfma_f32_16x16x32_bf16 v[62:65], v[146:149], v[178:181], v[62:65]
	v_mfma_f32_16x16x32_bf16 v[58:61], v[154:157], v[178:181], v[58:61]
	v_mfma_f32_16x16x32_bf16 v[54:57], v[146:149], v[186:189], v[54:57]
	v_mfma_f32_16x16x32_bf16 v[50:53], v[154:157], v[186:189], v[50:53]
	v_mfma_f32_16x16x32_bf16 v[42:45], v[146:149], v[198:201], v[42:45]
	v_mfma_f32_16x16x32_bf16 v[34:37], v[154:157], v[198:201], v[34:37]
	v_mfma_f32_16x16x32_bf16 v[26:29], v[146:149], v[206:209], v[26:29]
	v_mfma_f32_16x16x32_bf16 v[18:21], v[154:157], v[206:209], v[18:21]
	s_setprio 0
	s_setprio 1
	v_mfma_f32_16x16x32_bf16 v[46:49], v[158:161], v[174:177], v[46:49]
	v_mfma_f32_16x16x32_bf16 v[38:41], v[166:169], v[174:177], v[38:41]
	v_mfma_f32_16x16x32_bf16 v[30:33], v[158:161], v[182:185], v[30:33]
	v_mfma_f32_16x16x32_bf16 v[22:25], v[166:169], v[182:185], v[22:25]
	v_mfma_f32_16x16x32_bf16 v[14:17], v[158:161], v[190:193], v[14:17]
	v_mfma_f32_16x16x32_bf16 v[10:13], v[166:169], v[190:193], v[10:13]
	v_mfma_f32_16x16x32_bf16 v[6:9], v[158:161], v[202:205], v[6:9]
	v_mfma_f32_16x16x32_bf16 v[2:5], v[166:169], v[202:205], v[2:5]
	v_mfma_f32_16x16x32_bf16 v[46:49], v[162:165], v[178:181], v[46:49]
	v_mfma_f32_16x16x32_bf16 v[38:41], v[170:173], v[178:181], v[38:41]
	v_mfma_f32_16x16x32_bf16 v[30:33], v[162:165], v[186:189], v[30:33]
	v_mfma_f32_16x16x32_bf16 v[22:25], v[170:173], v[186:189], v[22:25]
	v_mfma_f32_16x16x32_bf16 v[14:17], v[162:165], v[198:201], v[14:17]
	v_mfma_f32_16x16x32_bf16 v[10:13], v[170:173], v[198:201], v[10:13]
	v_mfma_f32_16x16x32_bf16 v[6:9], v[162:165], v[206:209], v[6:9]
	v_mfma_f32_16x16x32_bf16 v[2:5], v[170:173], v[206:209], v[2:5]
	s_setprio 0
	s_barrier
	s_add_u32 s30, s30, 0x100
	s_addc_u32 s31, s31, 0
	s_add_u32 s65, s65, 0x100
	s_addc_u32 s86, s86, 0
	s_cmp_ge_u32 s87, s4
	s_mov_b32 s38, s87
	s_cbranch_scc1 .Lpeel_done_833

;     __device__ __forceinline__ void operator()(const f32x4 (&acc)[2][2][4][2], const Unit& u, int wr, int wc, int fr, int fq) const {
;         const int kh = u.pn >> 2, row0 = (u.pm & 7) * BM + wr * 64 + fr, col0 = (u.pn & 3) * BM + wc * 32 + 4 * fq;
;         float* base = P + ((size_t)kh * 2048 + row0) * 1024 + col0;
; #pragma unroll
;         for (int ai = 0; ai < 2; ++ai)
; #pragma unroll
;             for (int m = 0; m < 4; ++m)
; #pragma unroll
;                 for (int bj = 0; bj < 2; ++bj)
; #pragma unroll
;                     for (int n = 0; n < 2; ++n) *(f32x4*)(base + (size_t)(ai * HALF + m * 16) * 1024 + bj * HALF + n * 16) = acc[ai][bj][m][n];
; template <class Epi, class Sched, bool ALIGN_EPI = false, bool SP2 = false>
; __device__ __forceinline__ void gemm_phase(PG8_LAS unsigned char* lds, const Gemm g, const Sched& S, const Epi& E) {
;     ...
;         cur = nxt; cA = nA; cB = nB; ++ui;
.Lpeel_done_833:
	s_lshl_b32 s31, s49, 8
	s_and_b32 s31, s31, 0x700
	v_add_u32_e32 v142, s31, v138
	s_lshl_b32 s31, s48, 8
	s_ashr_i32 s30, s48, 2
	s_and_b32 s31, s31, 0x300
	v_or_b32_e32 v0, s31, v140
	s_ashr_i32 s31, s30, 31
	s_lshl_b64 s[30:31], s[30:31], 23
	v_ashrrev_i32_e32 v143, 31, v142
	s_add_u32 s30, s46, s30
	s_addc_u32 s31, s47, s31
	v_lshlrev_b64 v[142:143], 12, v[142:143]
	v_lshl_add_u64 v[142:143], s[30:31], 0, v[142:143]
	v_lshlrev_b32_e32 v0, 2, v0
	v_lshl_add_u64 v[142:143], v[142:143], 0, v[0:1]
	s_mov_b32 s30, 0x10000
	global_store_dwordx4 v[142:143], v[126:129], off
	global_store_dwordx4 v[142:143], v[122:125], off offset:64
	global_store_dwordx4 v[142:143], v[106:109], off offset:512
	global_store_dwordx4 v[142:143], v[98:101], off offset:576
	s_mov_b32 s48, s63
	s_mov_b32 s49, s55
	v_add_co_u32_e32 v98, vcc, s30, v142
	s_mov_b32 s30, 0x20000
	s_nop 0
	v_addc_co_u32_e32 v99, vcc, 0, v143, vcc
	global_store_dwordx4 v[98:99], v[118:121], off
	global_store_dwordx4 v[98:99], v[114:117], off offset:64
	global_store_dwordx4 v[98:99], v[94:97], off offset:512
	global_store_dwordx4 v[98:99], v[86:89], off offset:576
	s_mov_b64 s[38:39], s[6:7]
	s_nop 0
	v_add_co_u32_e32 v86, vcc, s30, v142
	s_mov_b32 s30, 0x30000
	s_nop 0
	v_addc_co_u32_e32 v87, vcc, 0, v143, vcc
	global_store_dwordx4 v[86:87], v[110:113], off
	global_store_dwordx4 v[86:87], v[102:105], off offset:64
	global_store_dwordx4 v[86:87], v[78:81], off offset:512
	global_store_dwordx4 v[86:87], v[74:77], off offset:576
	s_nop 1
	v_add_co_u32_e32 v74, vcc, s30, v142
	s_mov_b32 s30, 0x80000
	s_nop 0
	v_addc_co_u32_e32 v75, vcc, 0, v143, vcc
	global_store_dwordx4 v[74:75], v[90:93], off
	global_store_dwordx4 v[74:75], v[82:85], off offset:64
	global_store_dwordx4 v[74:75], v[70:73], off offset:512
	global_store_dwordx4 v[74:75], v[66:69], off offset:576
	s_nop 1
	v_add_co_u32_e32 v66, vcc, s30, v142
	s_mov_b32 s30, 0x90000
	s_nop 0
	v_addc_co_u32_e32 v67, vcc, 0, v143, vcc
	global_store_dwordx4 v[66:67], v[62:65], off
	global_store_dwordx4 v[66:67], v[58:61], off offset:64
	global_store_dwordx4 v[66:67], v[46:49], off offset:512
	global_store_dwordx4 v[66:67], v[38:41], off offset:576
	s_nop 1
	v_add_co_u32_e32 v38, vcc, s30, v142
	s_mov_b64 s[30:31], s[20:21]
	s_nop 0
	v_addc_co_u32_e32 v39, vcc, 0, v143, vcc
	global_store_dwordx4 v[38:39], v[54:57], off
	global_store_dwordx4 v[38:39], v[50:53], off offset:64
	global_store_dwordx4 v[38:39], v[30:33], off offset:512
	global_store_dwordx4 v[38:39], v[22:25], off offset:576
	s_nop 1
	v_add_co_u32_e32 v22, vcc, 0xa0000, v142
	s_nop 1
	v_addc_co_u32_e32 v23, vcc, 0, v143, vcc
	global_store_dwordx4 v[22:23], v[42:45], off
	global_store_dwordx4 v[22:23], v[34:37], off offset:64
	global_store_dwordx4 v[22:23], v[14:17], off offset:512
	global_store_dwordx4 v[22:23], v[10:13], off offset:576
	s_nop 1
	v_add_co_u32_e32 v10, vcc, 0xb0000, v142
	s_nop 1
	v_addc_co_u32_e32 v11, vcc, 0, v143, vcc
	s_and_b64 vcc, exec, s[10:11]
	global_store_dwordx4 v[10:11], v[26:29], off
	global_store_dwordx4 v[10:11], v[18:21], off offset:64
	global_store_dwordx4 v[10:11], v[6:9], off offset:512
	global_store_dwordx4 v[10:11], v[2:5], off offset:576
	s_cbranch_vccz .LBB0_826
	s_waitcnt vmcnt(0)
	s_cmpk_gt_u32 s25, 0xff
	s_cbranch_scc1 .LBB0_837
	s_barrier

; #define PG8_STAGE(bufoff, gbase, voff) do { _Pragma("unroll") for (int _i = 0; _i < 2; ++_i) \
;         __builtin_amdgcn_global_load_lds((const unsigned*)((const char*)(gbase) + (voff)[_i]), (PG8_LAS unsigned*)(lds + (bufoff) + ldsw + _i * 8192), 16, 0, 0); } while (0)
; #define PG8_LDA(dst, b, h) do { _Pragma("unroll") for (int m = 0; m < 4; ++m) _Pragma("unroll") for (int k = 0; k < 2; ++k) dst[m][k] = *(const PG8_LAS bf16x8*)(lds + PG8_SA(b, h) + aoff + m * 2048 + k * 1024); } while (0)
; #define PG8_LDB(dst, b, h) do { _Pragma("unroll") for (int n = 0; n < 2; ++n) _Pragma("unroll") for (int k = 0; k < 2; ++k) dst[n][k] = *(const PG8_LAS bf16x8*)(lds + PG8_SB(b, h) + boff + n * 2048 + k * 1024); } while (0)
; #define PG8_MMA(ai, bj, At, Bt) do { __builtin_amdgcn_s_setprio(1); _Pragma("unroll") for (int m = 0; m < 4; ++m) _Pragma("unroll") for (int n = 0; n < 2; ++n) _Pragma("unroll") for (int k = 0; k < 2; ++k) \
;         acc[ai][bj][m][n] = __builtin_amdgcn_mfma_f32_16x16x32_bf16(Bt[n][k], At[m][k], acc[ai][bj][m][n], 0, 0, 0); __builtin_amdgcn_s_setprio(0); } while (0)
; #define PG8_WAIT_V(n) asm volatile("s_waitcnt vmcnt(" #n ")" ::: "memory")
; #define PG8_WAIT_L(n) asm volatile("s_waitcnt lgkmcnt(" #n ")" ::: "memory")
; #define PG8_BAR __builtin_amdgcn_s_barrier()
; #define PG8_SCHED __builtin_amdgcn_sched_barrier(0)
; template <class Epi, class Sched, bool ALIGN_EPI = false, bool SP2 = false>
; __device__ __forceinline__ void gemm_phase(PG8_LAS unsigned char* lds, const Gemm g, const Sched& S, const Epi& E) {
;     ...
;             PG8_LDB(B0, 0, 0); PG8_LDB(B1, 0, 1); PG8_SCHED; PG8_LDA(At, 0, 0); PG8_STAGE(PG8_SA(1, 1), a1 + hstep, voffA);
;             PG8_WAIT_V(8); PG8_WAIT_L(0); PG8_BAR; PG8_MMA(0, 0, At, B0); PG8_MMA(0, 1, At, B1); PG8_BAR; PG8_SCHED;
;             PG8_LDA(At, 0, 1); PG8_STAGE(PG8_SB(0, 0), b2, voffB); PG8_STAGE(PG8_SB(0, 1), b2 + hstep, voffB); PG8_STAGE(PG8_SA(0, 0), a2, voffA);
;             PG8_WAIT_V(8); PG8_WAIT_L(0); PG8_BAR; PG8_MMA(1, 0, At, B0); PG8_MMA(1, 1, At, B1); PG8_BAR; PG8_SCHED;
.LBB0_1179:
	s_ashr_i32 s21, s20, 31
	s_lshl_b64 s[30:31], s[20:21], 19
	s_add_u32 s30, s77, s30
	s_addc_u32 s31, s26, s31
	s_and_b64 s[38:39], s[6:7], exec
	s_cselect_b32 s21, s31, s43
	s_cselect_b32 s29, s30, s42
	s_ashr_i32 s19, s18, 31
	s_lshl_b64 s[38:39], s[18:19], 19
	s_add_u32 s38, s22, s38
	s_addc_u32 s39, s23, s39
	s_and_b64 s[46:47], s[6:7], exec
	s_cselect_b32 s19, s39, s45
	s_cselect_b32 s41, s38, s44
	s_add_u32 s42, s42, 0x40080
	s_addc_u32 s43, s43, 0
	s_add_u32 s73, s44, 0x100
	s_addc_u32 s78, s45, 0
	s_mov_b32 s79, -2
	s_add_u32 s44, s42, 0xfffc0080
	s_addc_u32 s45, s43, -1
	s_add_i32 s86, 0, 0x10000
	s_cmp_eq_u32 s79, 12
	s_cselect_b32 s47, s21, s45
	s_cselect_b32 s46, s29, s44
	v_add_u32_e32 v0, s86, v145
	s_cselect_b32 s45, s19, s78
	s_cselect_b32 s44, s41, s73
	s_add_i32 s93, 0, 0x14000
	ds_read_b128 v[148:151], v0
	ds_read_b128 v[152:155], v0 offset:1024
	ds_read_b128 v[156:159], v0 offset:2048
	ds_read_b128 v[160:163], v0 offset:3072
	v_add_u32_e32 v0, s93, v145
	ds_read_b128 v[164:167], v0
	ds_read_b128 v[168:171], v0 offset:1024
	ds_read_b128 v[172:175], v0 offset:2048
	ds_read_b128 v[176:179], v0 offset:3072
	v_lshl_add_u64 v[142:143], s[42:43], 0, v[138:139]
	s_add_i32 m0, s49, 0xc000
	ds_read_b128 v[180:183], v147
	ds_read_b128 v[184:187], v147 offset:1024
	ds_read_b128 v[188:191], v147 offset:2048
	ds_read_b128 v[198:201], v147 offset:3072
	ds_read_b128 v[202:205], v147 offset:4096
	ds_read_b128 v[206:209], v147 offset:5120
	ds_read_b128 v[210:213], v147 offset:6144
	ds_read_b128 v[214:217], v147 offset:7168
	global_load_lds_dwordx4 v[142:143], off
	v_lshl_add_u64 v[142:143], s[42:43], 0, v[140:141]
	s_add_i32 m0, s49, 0xe000
	s_nop 0
	global_load_lds_dwordx4 v[142:143], off
	s_waitcnt vmcnt(8)
	s_waitcnt lgkmcnt(0)
	s_barrier
	s_setprio 1
	s_waitcnt lgkmcnt(0)
	v_mfma_f32_16x16x32_bf16 v[126:129], v[148:151], v[180:183], 0
	v_mfma_f32_16x16x32_bf16 v[118:121], v[156:159], v[180:183], 0
	v_mfma_f32_16x16x32_bf16 v[110:113], v[148:151], v[188:191], 0
	v_mfma_f32_16x16x32_bf16 v[102:105], v[156:159], v[188:191], 0
	v_mfma_f32_16x16x32_bf16 v[94:97], v[148:151], v[202:205], 0
	v_mfma_f32_16x16x32_bf16 v[86:89], v[156:159], v[202:205], 0
	v_mfma_f32_16x16x32_bf16 v[78:81], v[148:151], v[210:213], 0
	v_mfma_f32_16x16x32_bf16 v[70:73], v[156:159], v[210:213], 0
	v_mfma_f32_16x16x32_bf16 v[126:129], v[152:155], v[184:187], v[126:129]
	v_mfma_f32_16x16x32_bf16 v[118:121], v[160:163], v[184:187], v[118:121]
	v_mfma_f32_16x16x32_bf16 v[110:113], v[152:155], v[198:201], v[110:113]
	v_mfma_f32_16x16x32_bf16 v[102:105], v[160:163], v[198:201], v[102:105]
	v_mfma_f32_16x16x32_bf16 v[94:97], v[152:155], v[206:209], v[94:97]
	v_mfma_f32_16x16x32_bf16 v[86:89], v[160:163], v[206:209], v[86:89]
	v_mfma_f32_16x16x32_bf16 v[78:81], v[152:155], v[214:217], v[78:81]
	v_mfma_f32_16x16x32_bf16 v[70:73], v[160:163], v[214:217], v[70:73]
	s_setprio 0
	s_setprio 1
	v_mfma_f32_16x16x32_bf16 v[122:125], v[164:167], v[180:183], 0
	v_mfma_f32_16x16x32_bf16 v[114:117], v[172:175], v[180:183], 0
	v_mfma_f32_16x16x32_bf16 v[106:109], v[164:167], v[188:191], 0
	v_mfma_f32_16x16x32_bf16 v[98:101], v[172:175], v[188:191], 0
	v_mfma_f32_16x16x32_bf16 v[90:93], v[164:167], v[202:205], 0
	v_mfma_f32_16x16x32_bf16 v[82:85], v[172:175], v[202:205], 0
	v_mfma_f32_16x16x32_bf16 v[74:77], v[164:167], v[210:213], 0
	v_mfma_f32_16x16x32_bf16 v[66:69], v[172:175], v[210:213], 0
	v_mfma_f32_16x16x32_bf16 v[122:125], v[168:171], v[184:187], v[122:125]
	v_mfma_f32_16x16x32_bf16 v[114:117], v[176:179], v[184:187], v[114:117]
	v_mfma_f32_16x16x32_bf16 v[106:109], v[168:171], v[198:201], v[106:109]
	v_mfma_f32_16x16x32_bf16 v[98:101], v[176:179], v[198:201], v[98:101]
	v_mfma_f32_16x16x32_bf16 v[90:93], v[168:171], v[206:209], v[90:93]
	v_mfma_f32_16x16x32_bf16 v[82:85], v[176:179], v[206:209], v[82:85]
	v_mfma_f32_16x16x32_bf16 v[74:77], v[168:171], v[214:217], v[74:77]
	v_mfma_f32_16x16x32_bf16 v[66:69], v[176:179], v[214:217], v[66:69]
	s_setprio 0
	s_barrier
	s_add_i32 s86, s86, s25
	v_lshl_add_u64 v[142:143], s[44:45], 0, v[134:135]
	s_mov_b32 m0, s86
	ds_read_b128 v[180:183], v147 offset:16384
	ds_read_b128 v[184:187], v147 offset:17408
	ds_read_b128 v[188:191], v147 offset:18432
	ds_read_b128 v[198:201], v147 offset:19456
	ds_read_b128 v[202:205], v147 offset:20480
	ds_read_b128 v[206:209], v147 offset:21504
	ds_read_b128 v[210:213], v147 offset:22528
	ds_read_b128 v[214:217], v147 offset:23552
	global_load_lds_dwordx4 v[142:143], off
	s_add_i32 m0, s86, 0x2000
	s_add_u32 s86, s44, 0x40000
	v_lshl_add_u64 v[192:193], s[44:45], 0, v[130:131]
	s_addc_u32 s87, s45, 0
	s_add_i32 s93, s93, s25
	global_load_lds_dwordx4 v[192:193], off
	v_lshl_add_u64 v[218:219], s[86:87], 0, v[134:135]
	s_mov_b32 m0, s93
	v_lshl_add_u64 v[220:221], s[46:47], 0, v[132:133]
	global_load_lds_dwordx4 v[218:219], off
	v_lshl_add_u64 v[218:219], s[86:87], 0, v[130:131]
	s_add_i32 m0, s93, 0x2000
	s_nop 0
	global_load_lds_dwordx4 v[218:219], off
	v_lshl_add_u64 v[218:219], s[46:47], 0, v[136:137]
	s_mov_b32 m0, s49
	s_nop 0
	global_load_lds_dwordx4 v[218:219], off
	s_mov_b32 m0, s50
	s_nop 0
	global_load_lds_dwordx4 v[220:221], off
	s_waitcnt vmcnt(8)
	s_waitcnt lgkmcnt(0)
	s_barrier
; #define PG8_STAGE(bufoff, gbase, voff) do { _Pragma("unroll") for (int _i = 0; _i < 2; ++_i) \
;         __builtin_amdgcn_global_load_lds((const unsigned*)((const char*)(gbase) + (voff)[_i]), (PG8_LAS unsigned*)(lds + (bufoff) + ldsw + _i * 8192), 16, 0, 0); } while (0)
; #define PG8_LDA(dst, b, h) do { _Pragma("unroll") for (int m = 0; m < 4; ++m) _Pragma("unroll") for (int k = 0; k < 2; ++k) dst[m][k] = *(const PG8_LAS bf16x8*)(lds + PG8_SA(b, h) + aoff + m * 2048 + k * 1024); } while (0)
; #define PG8_LDB(dst, b, h) do { _Pragma("unroll") for (int n = 0; n < 2; ++n) _Pragma("unroll") for (int k = 0; k < 2; ++k) dst[n][k] = *(const PG8_LAS bf16x8*)(lds + PG8_SB(b, h) + boff + n * 2048 + k * 1024); } while (0)
; #define PG8_MMA(ai, bj, At, Bt) do { __builtin_amdgcn_s_setprio(1); _Pragma("unroll") for (int m = 0; m < 4; ++m) _Pragma("unroll") for (int n = 0; n < 2; ++n) _Pragma("unroll") for (int k = 0; k < 2; ++k) \
;         acc[ai][bj][m][n] = __builtin_amdgcn_mfma_f32_16x16x32_bf16(Bt[n][k], At[m][k], acc[ai][bj][m][n], 0, 0, 0); __builtin_amdgcn_s_setprio(0); } while (0)
; #define PG8_WAIT_V(n) asm volatile("s_waitcnt vmcnt(" #n ")" ::: "memory")
; #define PG8_WAIT_L(n) asm volatile("s_waitcnt lgkmcnt(" #n ")" ::: "memory")
; #define PG8_BAR __builtin_amdgcn_s_barrier()
; #define PG8_SCHED __builtin_amdgcn_sched_barrier(0)
; template <class Epi, class Sched, bool ALIGN_EPI = false, bool SP2 = false>
; __device__ __forceinline__ void gemm_phase(PG8_LAS unsigned char* lds, const Gemm g, const Sched& S, const Epi& E) {
;     ...
;             PG8_WAIT_V(8); PG8_WAIT_L(0); PG8_BAR; PG8_MMA(1, 0, At, B0); PG8_MMA(1, 1, At, B1); PG8_BAR; PG8_SCHED;
;             PG8_LDB(B0, 1, 0); PG8_LDB(B1, 1, 1); PG8_SCHED; PG8_LDA(At, 1, 0); PG8_STAGE(PG8_SA(0, 1), a2 + hstep, voffA);
;             PG8_WAIT_V(8); PG8_WAIT_L(0); PG8_BAR; PG8_MMA(0, 0, At, B0); PG8_MMA(0, 1, At, B1); PG8_BAR; PG8_SCHED;
	s_setprio 1
	s_waitcnt lgkmcnt(0)
	v_mfma_f32_16x16x32_bf16 v[62:65], v[148:151], v[180:183], 0
	v_mfma_f32_16x16x32_bf16 v[54:57], v[156:159], v[180:183], 0
	v_mfma_f32_16x16x32_bf16 v[46:49], v[148:151], v[188:191], 0
	v_mfma_f32_16x16x32_bf16 v[38:41], v[156:159], v[188:191], 0
	v_mfma_f32_16x16x32_bf16 v[30:33], v[148:151], v[202:205], 0
	v_mfma_f32_16x16x32_bf16 v[22:25], v[156:159], v[202:205], 0
	v_mfma_f32_16x16x32_bf16 v[14:17], v[148:151], v[210:213], 0
	v_mfma_f32_16x16x32_bf16 v[6:9], v[156:159], v[210:213], 0
	v_mfma_f32_16x16x32_bf16 v[62:65], v[152:155], v[184:187], v[62:65]
	v_mfma_f32_16x16x32_bf16 v[54:57], v[160:163], v[184:187], v[54:57]
	v_mfma_f32_16x16x32_bf16 v[46:49], v[152:155], v[198:201], v[46:49]
	v_mfma_f32_16x16x32_bf16 v[38:41], v[160:163], v[198:201], v[38:41]
	v_mfma_f32_16x16x32_bf16 v[30:33], v[152:155], v[206:209], v[30:33]
	v_mfma_f32_16x16x32_bf16 v[22:25], v[160:163], v[206:209], v[22:25]
	v_mfma_f32_16x16x32_bf16 v[14:17], v[152:155], v[214:217], v[14:17]
	v_mfma_f32_16x16x32_bf16 v[6:9], v[160:163], v[214:217], v[6:9]
	s_setprio 0
	s_setprio 1
	v_mfma_f32_16x16x32_bf16 v[58:61], v[164:167], v[180:183], 0
	v_mfma_f32_16x16x32_bf16 v[50:53], v[172:175], v[180:183], 0
	v_mfma_f32_16x16x32_bf16 v[42:45], v[164:167], v[188:191], 0
	v_mfma_f32_16x16x32_bf16 v[34:37], v[172:175], v[188:191], 0
	v_mfma_f32_16x16x32_bf16 v[26:29], v[164:167], v[202:205], 0
	v_mfma_f32_16x16x32_bf16 v[18:21], v[172:175], v[202:205], 0
	v_mfma_f32_16x16x32_bf16 v[10:13], v[164:167], v[210:213], 0
	v_mfma_f32_16x16x32_bf16 v[2:5], v[172:175], v[210:213], 0
	v_mfma_f32_16x16x32_bf16 v[58:61], v[168:171], v[184:187], v[58:61]
	v_mfma_f32_16x16x32_bf16 v[50:53], v[176:179], v[184:187], v[50:53]
	v_mfma_f32_16x16x32_bf16 v[42:45], v[168:171], v[198:201], v[42:45]
	v_mfma_f32_16x16x32_bf16 v[34:37], v[176:179], v[198:201], v[34:37]
	v_mfma_f32_16x16x32_bf16 v[26:29], v[168:171], v[206:209], v[26:29]
	v_mfma_f32_16x16x32_bf16 v[18:21], v[176:179], v[206:209], v[18:21]
	v_mfma_f32_16x16x32_bf16 v[10:13], v[168:171], v[214:217], v[10:13]
	v_mfma_f32_16x16x32_bf16 v[2:5], v[176:179], v[214:217], v[2:5]
	s_setprio 0
	s_barrier
	s_add_i32 s86, 0, 0x18000
	v_add_u32_e32 v0, s86, v145
	s_add_i32 s87, 0, 0x1c000
	ds_read_b128 v[148:151], v0
	ds_read_b128 v[152:155], v0 offset:1024
	ds_read_b128 v[156:159], v0 offset:2048
	ds_read_b128 v[160:163], v0 offset:3072
	v_add_u32_e32 v0, s87, v145
	ds_read_b128 v[164:167], v0
	ds_read_b128 v[168:171], v0 offset:1024
	ds_read_b128 v[172:175], v0 offset:2048
	ds_read_b128 v[176:179], v0 offset:3072
	s_add_u32 s46, s46, 0x40000
	s_addc_u32 s47, s47, 0
	s_mov_b32 m0, s51
	v_lshl_add_u64 v[222:223], s[46:47], 0, v[136:137]
	ds_read_b128 v[180:183], v147 offset:32768
	ds_read_b128 v[184:187], v147 offset:33792
	ds_read_b128 v[188:191], v147 offset:34816
	ds_read_b128 v[198:201], v147 offset:35840
	ds_read_b128 v[202:205], v147 offset:36864
	ds_read_b128 v[206:209], v147 offset:37888
	ds_read_b128 v[210:213], v147 offset:38912
	ds_read_b128 v[214:217], v147 offset:39936
	global_load_lds_dwordx4 v[222:223], off
	v_lshl_add_u64 v[222:223], s[46:47], 0, v[132:133]
	s_mov_b32 m0, s54
	s_nop 0
	global_load_lds_dwordx4 v[222:223], off
	s_waitcnt vmcnt(8)
	s_waitcnt lgkmcnt(0)
	s_barrier
	s_setprio 1
	s_waitcnt lgkmcnt(0)
	v_mfma_f32_16x16x32_bf16 v[126:129], v[148:151], v[180:183], v[126:129]
	v_mfma_f32_16x16x32_bf16 v[118:121], v[156:159], v[180:183], v[118:121]
	v_mfma_f32_16x16x32_bf16 v[110:113], v[148:151], v[188:191], v[110:113]
	v_mfma_f32_16x16x32_bf16 v[102:105], v[156:159], v[188:191], v[102:105]
	v_mfma_f32_16x16x32_bf16 v[94:97], v[148:151], v[202:205], v[94:97]
	v_mfma_f32_16x16x32_bf16 v[86:89], v[156:159], v[202:205], v[86:89]
	v_mfma_f32_16x16x32_bf16 v[78:81], v[148:151], v[210:213], v[78:81]
	v_mfma_f32_16x16x32_bf16 v[70:73], v[156:159], v[210:213], v[70:73]
	v_mfma_f32_16x16x32_bf16 v[126:129], v[152:155], v[184:187], v[126:129]
	v_mfma_f32_16x16x32_bf16 v[118:121], v[160:163], v[184:187], v[118:121]
	v_mfma_f32_16x16x32_bf16 v[110:113], v[152:155], v[198:201], v[110:113]
	v_mfma_f32_16x16x32_bf16 v[102:105], v[160:163], v[198:201], v[102:105]
	v_mfma_f32_16x16x32_bf16 v[94:97], v[152:155], v[206:209], v[94:97]
	v_mfma_f32_16x16x32_bf16 v[86:89], v[160:163], v[206:209], v[86:89]
	v_mfma_f32_16x16x32_bf16 v[78:81], v[152:155], v[214:217], v[78:81]
	v_mfma_f32_16x16x32_bf16 v[70:73], v[160:163], v[214:217], v[70:73]
	s_setprio 0
	s_setprio 1
	v_mfma_f32_16x16x32_bf16 v[122:125], v[164:167], v[180:183], v[122:125]
	v_mfma_f32_16x16x32_bf16 v[114:117], v[172:175], v[180:183], v[114:117]
	v_mfma_f32_16x16x32_bf16 v[106:109], v[164:167], v[188:191], v[106:109]
	v_mfma_f32_16x16x32_bf16 v[98:101], v[172:175], v[188:191], v[98:101]
	v_mfma_f32_16x16x32_bf16 v[90:93], v[164:167], v[202:205], v[90:93]
	v_mfma_f32_16x16x32_bf16 v[82:85], v[172:175], v[202:205], v[82:85]
	v_mfma_f32_16x16x32_bf16 v[74:77], v[164:167], v[210:213], v[74:77]
	v_mfma_f32_16x16x32_bf16 v[66:69], v[172:175], v[210:213], v[66:69]
	v_mfma_f32_16x16x32_bf16 v[122:125], v[168:171], v[184:187], v[122:125]
	v_mfma_f32_16x16x32_bf16 v[114:117], v[176:179], v[184:187], v[114:117]
	v_mfma_f32_16x16x32_bf16 v[106:109], v[168:171], v[198:201], v[106:109]
	v_mfma_f32_16x16x32_bf16 v[98:101], v[176:179], v[198:201], v[98:101]
	v_mfma_f32_16x16x32_bf16 v[90:93], v[168:171], v[206:209], v[90:93]
	v_mfma_f32_16x16x32_bf16 v[82:85], v[176:179], v[206:209], v[82:85]
	v_mfma_f32_16x16x32_bf16 v[74:77], v[168:171], v[214:217], v[74:77]
	v_mfma_f32_16x16x32_bf16 v[66:69], v[176:179], v[214:217], v[66:69]
	s_setprio 0
	s_barrier
; #define PG8_STAGE(bufoff, gbase, voff) do { _Pragma("unroll") for (int _i = 0; _i < 2; ++_i) \
;         __builtin_amdgcn_global_load_lds((const unsigned*)((const char*)(gbase) + (voff)[_i]), (PG8_LAS unsigned*)(lds + (bufoff) + ldsw + _i * 8192), 16, 0, 0); } while (0)
; #define PG8_LDA(dst, b, h) do { _Pragma("unroll") for (int m = 0; m < 4; ++m) _Pragma("unroll") for (int k = 0; k < 2; ++k) dst[m][k] = *(const PG8_LAS bf16x8*)(lds + PG8_SA(b, h) + aoff + m * 2048 + k * 1024); } while (0)
; #define PG8_MMA(ai, bj, At, Bt) do { __builtin_amdgcn_s_setprio(1); _Pragma("unroll") for (int m = 0; m < 4; ++m) _Pragma("unroll") for (int n = 0; n < 2; ++n) _Pragma("unroll") for (int k = 0; k < 2; ++k) \
;         acc[ai][bj][m][n] = __builtin_amdgcn_mfma_f32_16x16x32_bf16(Bt[n][k], At[m][k], acc[ai][bj][m][n], 0, 0, 0); __builtin_amdgcn_s_setprio(0); } while (0)
; #define PG8_WAIT_V(n) asm volatile("s_waitcnt vmcnt(" #n ")" ::: "memory")
; #define PG8_WAIT_L(n) asm volatile("s_waitcnt lgkmcnt(" #n ")" ::: "memory")
; #define PG8_BAR __builtin_amdgcn_s_barrier()
; #define PG8_SCHED __builtin_amdgcn_sched_barrier(0)
; template <class Epi, class Sched, bool ALIGN_EPI = false, bool SP2 = false>
; __device__ __forceinline__ void gemm_phase(PG8_LAS unsigned char* lds, const Gemm g, const Sched& S, const Epi& E) {
;     ...
;             PG8_LDA(At, 1, 1); PG8_STAGE(PG8_SB(1, 0), b3, voffB); PG8_STAGE(PG8_SB(1, 1), b3 + hstep, voffB); PG8_STAGE(PG8_SA(1, 0), a3, voffA);
;             PG8_WAIT_V(8); PG8_WAIT_L(0); PG8_BAR; PG8_MMA(1, 0, At, B0); PG8_MMA(1, 1, At, B1); PG8_BAR; PG8_SCHED;
	s_add_i32 s46, s86, s25
	v_lshl_add_u64 v[142:143], v[142:143], 0, s[58:59]
	s_mov_b32 m0, s46
	ds_read_b128 v[180:183], v147 offset:49152
	ds_read_b128 v[184:187], v147 offset:50176
	ds_read_b128 v[188:191], v147 offset:51200
	ds_read_b128 v[198:201], v147 offset:52224
	ds_read_b128 v[202:205], v147 offset:53248
	ds_read_b128 v[206:209], v147 offset:54272
	ds_read_b128 v[210:213], v147 offset:55296
	ds_read_b128 v[214:217], v147 offset:56320
	global_load_lds_dwordx4 v[142:143], off
	s_add_i32 m0, s46, 0x2000
	s_add_u32 s44, s44, 0x40080
	v_lshl_add_u64 v[142:143], v[192:193], 0, s[58:59]
	s_addc_u32 s45, s45, 0
	s_add_i32 s46, s87, s25
	global_load_lds_dwordx4 v[142:143], off
	v_lshl_add_u64 v[142:143], s[44:45], 0, v[134:135]
	s_mov_b32 m0, s46
	s_nop 0
	global_load_lds_dwordx4 v[142:143], off
	v_lshl_add_u64 v[142:143], s[44:45], 0, v[130:131]
	s_add_i32 m0, s46, 0x2000
	s_nop 0
	global_load_lds_dwordx4 v[142:143], off
	v_lshl_add_u64 v[142:143], v[218:219], 0, s[58:59]
	s_mov_b32 m0, s55
	s_nop 0
	global_load_lds_dwordx4 v[142:143], off
	v_lshl_add_u64 v[142:143], v[220:221], 0, s[58:59]
	s_mov_b32 m0, s63
	s_nop 0
	global_load_lds_dwordx4 v[142:143], off
	s_waitcnt vmcnt(8)
	s_waitcnt lgkmcnt(0)
	s_barrier
	s_setprio 1
	s_waitcnt lgkmcnt(0)
	v_mfma_f32_16x16x32_bf16 v[62:65], v[148:151], v[180:183], v[62:65]
	v_mfma_f32_16x16x32_bf16 v[54:57], v[156:159], v[180:183], v[54:57]
	v_mfma_f32_16x16x32_bf16 v[46:49], v[148:151], v[188:191], v[46:49]
	v_mfma_f32_16x16x32_bf16 v[38:41], v[156:159], v[188:191], v[38:41]
	v_mfma_f32_16x16x32_bf16 v[30:33], v[148:151], v[202:205], v[30:33]
	v_mfma_f32_16x16x32_bf16 v[22:25], v[156:159], v[202:205], v[22:25]
	v_mfma_f32_16x16x32_bf16 v[14:17], v[148:151], v[210:213], v[14:17]
	v_mfma_f32_16x16x32_bf16 v[6:9], v[156:159], v[210:213], v[6:9]
	v_mfma_f32_16x16x32_bf16 v[62:65], v[152:155], v[184:187], v[62:65]
	v_mfma_f32_16x16x32_bf16 v[54:57], v[160:163], v[184:187], v[54:57]
	v_mfma_f32_16x16x32_bf16 v[46:49], v[152:155], v[198:201], v[46:49]
	v_mfma_f32_16x16x32_bf16 v[38:41], v[160:163], v[198:201], v[38:41]
	v_mfma_f32_16x16x32_bf16 v[30:33], v[152:155], v[206:209], v[30:33]
	v_mfma_f32_16x16x32_bf16 v[22:25], v[160:163], v[206:209], v[22:25]
	v_mfma_f32_16x16x32_bf16 v[14:17], v[152:155], v[214:217], v[14:17]
	v_mfma_f32_16x16x32_bf16 v[6:9], v[160:163], v[214:217], v[6:9]
	s_setprio 0
	s_setprio 1
	v_mfma_f32_16x16x32_bf16 v[58:61], v[164:167], v[180:183], v[58:61]
	v_mfma_f32_16x16x32_bf16 v[50:53], v[172:175], v[180:183], v[50:53]
	v_mfma_f32_16x16x32_bf16 v[42:45], v[164:167], v[188:191], v[42:45]
	v_mfma_f32_16x16x32_bf16 v[34:37], v[172:175], v[188:191], v[34:37]
	v_mfma_f32_16x16x32_bf16 v[26:29], v[164:167], v[202:205], v[26:29]
	v_mfma_f32_16x16x32_bf16 v[18:21], v[172:175], v[202:205], v[18:21]
	v_mfma_f32_16x16x32_bf16 v[10:13], v[164:167], v[210:213], v[10:13]
	v_mfma_f32_16x16x32_bf16 v[2:5], v[172:175], v[210:213], v[2:5]
	v_mfma_f32_16x16x32_bf16 v[58:61], v[168:171], v[184:187], v[58:61]
	v_mfma_f32_16x16x32_bf16 v[50:53], v[176:179], v[184:187], v[50:53]
	v_mfma_f32_16x16x32_bf16 v[42:45], v[168:171], v[198:201], v[42:45]
	v_mfma_f32_16x16x32_bf16 v[34:37], v[176:179], v[198:201], v[34:37]
	v_mfma_f32_16x16x32_bf16 v[26:29], v[168:171], v[206:209], v[26:29]
	v_mfma_f32_16x16x32_bf16 v[18:21], v[176:179], v[206:209], v[18:21]
	v_mfma_f32_16x16x32_bf16 v[10:13], v[168:171], v[214:217], v[10:13]
	v_mfma_f32_16x16x32_bf16 v[2:5], v[176:179], v[214:217], v[2:5]
	s_setprio 0
	s_barrier
	s_add_i32 s79, s79, 2
	s_add_u32 s42, s42, 0x100
	s_addc_u32 s43, s43, 0
	s_add_u32 s73, s73, 0x100
	s_addc_u32 s78, s78, 0
	s_cmp_gt_u32 s79, 13
	s_cbranch_scc1 .Lpeel_done_1180

; #define PG8_BAR __builtin_amdgcn_s_barrier()
; template <class Epi, class Sched, bool ALIGN_EPI = false, bool SP2 = false>
; __device__ __forceinline__ void gemm_phase(PG8_LAS unsigned char* lds, const Gemm g, const Sched& S, const Epi& E) {
;     ...
;         if constexpr (ALIGN_EPI) { if (wr == 0) PG8_BAR; }
;         if constexpr (!Epi::AFTER_DRAIN) { E(acc, cur, wr, wc, fr, fq); S.done(cur); }
.Lpeel_done_1180:
	s_and_b64 vcc, exec, s[16:17]
	s_cbranch_vccz .LBB0_1183
	s_barrier
